# placement: FFN-F2 epilogue blocks after the first row half shifted by 8 bytes
# speedup vs baseline: 1.0081x; 1.0040x over previous
.LBB0_1060:
	s_lshl_b32 s0, s3, 8
	s_add_i32 s0, s0, s60
	s_cmpk_lt_i32 s0, 0x2000
	s_movk_i32 s20, 0xfff
	v_lshl_or_b32 v192, s2, 8, v223
	s_cselect_b32 s14, s20, 0x7ff
	s_or_b32 s2, s0, 63
	s_and_b32 s1, s14, s0
	s_and_b32 s15, s14, s2
	v_or_b32_e32 v226, s0, v221
	v_mov_b64_e32 v[208:209], s[10:11]
	s_movk_i32 s26, 0x2c00
	v_ashrrev_i32_e32 v193, 31, v192
	v_mad_i64_i32 v[152:153], s[2:3], v226, s26, v[208:209]
	s_cmp_eq_u32 s1, 0
	s_mul_i32 s1, s0, 0x2c00
	v_lshlrev_b64 v[204:205], 1, v[192:193]
	s_cselect_b64 s[62:63], -1, 0
	s_mul_hi_i32 s3, s0, 0x2c00
	s_add_u32 s2, s10, s1
	v_lshl_add_u64 v[194:195], v[152:153], 0, v[204:205]
	s_mov_b32 s21, 0x2c000
	s_addc_u32 s3, s11, s3
	v_add_co_u32_e32 v198, vcc, s21, v194
	s_and_b64 s[12:13], s[62:63], exec
	s_nop 0
	v_addc_co_u32_e32 v199, vcc, 0, v195, vcc
	s_mov_b32 s22, 0x58000
	s_cselect_b32 s12, 0, 0xffffd400
	s_cselect_b32 s13, 0, -1
	s_cmp_eq_u32 s15, s14
	v_add_co_u32_e32 v200, vcc, s22, v194
	s_cselect_b64 s[50:51], -1, 0
	v_lshlrev_b64 v[88:89], 2, v[192:193]
	v_addc_co_u32_e32 v201, vcc, 0, v195, vcc
	s_mov_b32 s23, 0x84000
	v_lshl_add_u64 v[202:203], s[2:3], 0, v[204:205]
	s_and_b64 s[2:3], s[50:51], exec
	v_lshl_add_u64 v[190:191], s[18:19], 0, v[88:89]
	v_lshl_add_u64 v[90:91], s[46:47], 0, v[88:89]
	v_lshl_add_u64 v[96:97], s[48:49], 0, v[88:89]
	v_add_co_u32_e32 v206, vcc, s23, v194
	s_cselect_b32 s72, 0, 0xb0000
	v_lshl_add_u64 v[188:189], s[30:31], 0, v[88:89]
	global_load_dwordx4 v[100:103], v[190:191], off offset:16
	global_load_dwordx4 v[120:123], v[190:191], off
	global_load_dwordx4 v[92:95], v[90:91], off offset:16
	global_load_dwordx4 v[112:115], v[90:91], off
	s_nop 0
	global_load_dwordx4 v[88:91], v[96:97], off offset:16
	global_load_dwordx4 v[108:111], v[96:97], off
	s_nop 0
	global_load_dwordx4 v[96:99], v[188:189], off offset:16
	global_load_dwordx4 v[116:119], v[188:189], off
	global_load_dwordx4 v[172:175], v[194:195], off
	v_addc_co_u32_e32 v207, vcc, 0, v195, vcc
	v_lshl_add_u64 v[196:197], v[202:203], 0, s[12:13]
	v_lshl_add_u64 v[202:203], v[202:203], 0, s[72:73]
	global_load_dwordx4 v[168:171], v[198:199], off
	global_load_dwordx4 v[164:167], v[200:201], off
	global_load_dwordx4 v[152:155], v[206:207], off
	global_load_dwordx4 v[232:235], v[202:203], off
	global_load_dwordx4 v[228:231], v[196:197], off
	v_or_b32_e32 v193, v211, v219
	v_lshlrev_b32_e32 v193, 2, v193
	v_or_b32_e32 v225, v219, v212
	v_lshlrev_b32_e32 v225, 2, v225
	s_add_i32 s12, s0, 0x80
	s_cmpk_lt_i32 s12, 0x2000
	s_cselect_b32 s13, s20, 0x7ff
	s_addk_i32 s0, 0xbf
	s_and_b32 s14, s13, s12
	s_and_b32 s15, s13, s0
	s_cmp_eq_u32 s14, 0
	s_waitcnt vmcnt(0)
	ds_bpermute_b32 v239, v193, v172
	ds_bpermute_b32 v240, v193, v173
	ds_bpermute_b32 v241, v193, v174
	ds_bpermute_b32 v242, v193, v175
	ds_bpermute_b32 v243, v225, v168
	ds_bpermute_b32 v244, v225, v169
	ds_bpermute_b32 v245, v225, v170
	v_cndmask_b32_e64 v227, v235, 0, s[50:51]
	v_cndmask_b32_e64 v236, v230, 0, s[62:63]
	v_cndmask_b32_e64 v237, v229, 0, s[62:63]
	v_cndmask_b32_e64 v229, v233, 0, s[50:51]
	v_cndmask_b32_e64 v230, v232, 0, s[50:51]
	ds_bpermute_b32 v232, v225, v172
	ds_bpermute_b32 v233, v225, v173
	v_cndmask_b32_e64 v238, v228, 0, s[62:63]
	v_cndmask_b32_e64 v228, v234, 0, s[50:51]
	ds_bpermute_b32 v234, v225, v174
	ds_bpermute_b32 v235, v225, v175
	ds_bpermute_b32 v246, v225, v171
	s_waitcnt lgkmcnt(11)
	v_cndmask_b32_e64 v238, v239, v238, s[4:5]
	s_waitcnt lgkmcnt(4)
	v_cndmask_b32_e64 v247, v232, v243, s[6:7]
	s_waitcnt lgkmcnt(3)
	v_cndmask_b32_e64 v249, v233, v244, s[6:7]
	v_lshlrev_b32_e32 v232, 16, v238
	v_and_b32_e32 v233, 0xffff0000, v238
	v_cndmask_b32_e64 v248, v240, v237, s[4:5]
	v_cndmask_b32_e64 v250, v241, v236, s[4:5]
	v_pk_mul_f32 v[232:233], v[120:121], v[232:233]
	v_lshlrev_b32_e32 v236, 16, v172
	v_and_b32_e32 v237, 0xffff0000, v172
	s_waitcnt lgkmcnt(2)
	v_cndmask_b32_e64 v251, v234, v245, s[6:7]
	s_waitcnt lgkmcnt(0)
	v_cndmask_b32_e64 v252, v235, v246, s[6:7]
	v_lshlrev_b32_e32 v234, 16, v247
	v_and_b32_e32 v235, 0xffff0000, v247
	v_pk_fma_f32 v[232:233], v[112:113], v[236:237], v[232:233]
	v_cndmask_b32_e64 v231, v231, 0, s[62:63]
	v_pk_fma_f32 v[232:233], v[108:109], v[234:235], v[232:233]
	v_cndmask_b32_e64 v231, v242, v231, s[4:5]
	v_pk_add_f32 v[232:233], v[116:117], v[232:233]
	ds_bpermute_b32 v236, v225, v166
	v_mul_f32_e32 v172, 0xbfb8aa3b, v232
	v_exp_f32_e32 v172, v172
	ds_bpermute_b32 v237, v225, v167
	v_add_f32_e32 v172, 1.0, v172
	v_rcp_f32_e32 v234, v172
	v_mul_f32_e32 v172, 0xbfb8aa3b, v233
	v_exp_f32_e32 v172, v172
	s_nop 0
	v_add_f32_e32 v172, 1.0, v172
	v_rcp_f32_e32 v235, v172
	v_lshlrev_b32_e32 v172, 16, v173
	v_and_b32_e32 v173, 0xffff0000, v173
	v_pk_mul_f32 v[232:233], v[232:233], v[234:235]
	s_nop 0
	v_pk_mul_f32 v[160:161], v[160:161], v[232:233]
	v_lshlrev_b32_e32 v232, 16, v248
	v_and_b32_e32 v233, 0xffff0000, v248
	v_pk_mul_f32 v[232:233], v[122:123], v[232:233]
	v_lshlrev_b32_e32 v234, 16, v249
	v_and_b32_e32 v235, 0xffff0000, v249
	v_pk_fma_f32 v[172:173], v[114:115], v[172:173], v[232:233]
	s_nop 0
	v_pk_fma_f32 v[172:173], v[110:111], v[234:235], v[172:173]
	v_lshlrev_b32_e32 v234, 16, v174
	v_pk_add_f32 v[172:173], v[118:119], v[172:173]
	v_and_b32_e32 v235, 0xffff0000, v174
	v_mul_f32_e32 v232, 0xbfb8aa3b, v172
	v_mul_f32_e32 v233, 0xbfb8aa3b, v173
	v_exp_f32_e32 v232, v232
	v_exp_f32_e32 v233, v233
	v_add_f32_e32 v232, 1.0, v232
	v_add_f32_e32 v233, 1.0, v233
	v_rcp_f32_e32 v232, v232
	v_rcp_f32_e32 v233, v233
	s_nop 0
	v_pk_mul_f32 v[172:173], v[172:173], v[232:233]
	s_nop 0
	v_pk_mul_f32 v[162:163], v[162:163], v[172:173]
	v_lshlrev_b32_e32 v172, 16, v250
	v_and_b32_e32 v173, 0xffff0000, v250
	v_pk_mul_f32 v[172:173], v[100:101], v[172:173]
	v_lshlrev_b32_e32 v232, 16, v251
	v_and_b32_e32 v233, 0xffff0000, v251
	v_pk_fma_f32 v[172:173], v[92:93], v[234:235], v[172:173]
	ds_bpermute_b32 v234, v225, v164
	v_pk_fma_f32 v[172:173], v[88:89], v[232:233], v[172:173]
	ds_bpermute_b32 v235, v225, v165
	v_pk_add_f32 v[172:173], v[96:97], v[172:173]
	s_nop 0
	v_mul_f32_e32 v174, 0xbfb8aa3b, v172
	v_exp_f32_e32 v174, v174
	s_nop 0
	v_add_f32_e32 v174, 1.0, v174
	v_rcp_f32_e32 v232, v174
	v_mul_f32_e32 v174, 0xbfb8aa3b, v173
	v_exp_f32_e32 v174, v174
	s_nop 0
	v_add_f32_e32 v174, 1.0, v174
	v_rcp_f32_e32 v233, v174
	v_lshlrev_b32_e32 v174, 16, v175
	v_and_b32_e32 v175, 0xffff0000, v175
	v_pk_mul_f32 v[172:173], v[172:173], v[232:233]
	s_nop 0
	v_pk_mul_f32 v[156:157], v[156:157], v[172:173]
	v_lshlrev_b32_e32 v172, 16, v231
	v_and_b32_e32 v173, 0xffff0000, v231
	v_pk_mul_f32 v[172:173], v[102:103], v[172:173]
	v_lshlrev_b32_e32 v232, 16, v252
	v_and_b32_e32 v233, 0xffff0000, v252
	v_pk_fma_f32 v[172:173], v[94:95], v[174:175], v[172:173]
	ds_bpermute_b32 v231, v193, v170
	v_pk_fma_f32 v[172:173], v[90:91], v[232:233], v[172:173]
	ds_bpermute_b32 v232, v193, v171
	v_pk_add_f32 v[172:173], v[98:99], v[172:173]
	v_or_b32_e32 v233, 16, v226
	v_mul_f32_e32 v174, 0xbfb8aa3b, v172
	v_mul_f32_e32 v175, 0xbfb8aa3b, v173
	v_exp_f32_e32 v174, v174
	v_exp_f32_e32 v175, v175
	s_waitcnt lgkmcnt(0)
	v_cndmask_b32_e64 v242, v232, v242, s[4:5]
	v_add_f32_e32 v174, 1.0, v174
	v_add_f32_e32 v175, 1.0, v175
	v_rcp_f32_e32 v174, v174
	v_rcp_f32_e32 v175, v175
	s_nop 0
	v_pk_mul_f32 v[172:173], v[172:173], v[174:175]
	ds_bpermute_b32 v174, v193, v168
	v_pk_mul_f32 v[172:173], v[158:159], v[172:173]
	v_cvt_pk_bf16_f32 v158, v160, v161
	v_cvt_pk_bf16_f32 v161, v172, v173
	v_mov_b64_e32 v[172:173], s[16:17]
	v_cvt_pk_bf16_f32 v160, v156, v157
	v_mad_i64_i32 v[156:157], s[2:3], v226, s26, v[172:173]
	v_cvt_pk_bf16_f32 v159, v162, v163
	v_lshl_add_u64 v[156:157], v[156:157], 0, v[204:205]
	global_store_dwordx4 v[156:157], v[158:161], off
	v_lshlrev_b32_e32 v162, 16, v168
	v_and_b32_e32 v163, 0xffff0000, v168
	s_waitcnt lgkmcnt(0)
	v_cndmask_b32_e64 v159, v174, v239, s[4:5]
	v_lshlrev_b32_e32 v158, 16, v159
	v_and_b32_e32 v159, 0xffff0000, v159
	v_cndmask_b32_e64 v161, v243, v234, s[6:7]
	v_pk_mul_f32 v[158:159], v[120:121], v[158:159]
	v_lshlrev_b32_e32 v160, 16, v161
	v_and_b32_e32 v161, 0xffff0000, v161
	v_pk_fma_f32 v[158:159], v[112:113], v[162:163], v[158:159]
	ds_bpermute_b32 v175, v193, v169
	v_pk_fma_f32 v[158:159], v[108:109], v[160:161], v[158:159]
	v_cndmask_b32_e64 v239, v244, v235, s[6:7]
	v_pk_add_f32 v[158:159], v[116:117], v[158:159]
	v_lshlrev_b32_e32 v162, 16, v169
	v_mul_f32_e32 v160, 0xbfb8aa3b, v158
	v_mul_f32_e32 v161, 0xbfb8aa3b, v159
	v_exp_f32_e32 v160, v160
	v_exp_f32_e32 v161, v161
	s_waitcnt lgkmcnt(0)
	v_cndmask_b32_e64 v238, v175, v240, s[4:5]
	v_and_b32_e32 v163, 0xffff0000, v169
	v_add_f32_e32 v160, 1.0, v160
	v_add_f32_e32 v161, 1.0, v161
	v_rcp_f32_e32 v160, v160
	v_rcp_f32_e32 v161, v161
	v_cndmask_b32_e64 v240, v231, v241, s[4:5]
	v_cndmask_b32_e64 v241, v245, v236, s[6:7]
	v_cndmask_b32_e64 v243, v246, v237, s[6:7]
	v_pk_mul_f32 v[158:159], v[158:159], v[160:161]
	v_lshlrev_b32_e32 v160, 16, v239
	v_pk_mul_f32 v[148:149], v[148:149], v[158:159]
	v_lshlrev_b32_e32 v158, 16, v238
	v_and_b32_e32 v159, 0xffff0000, v238
	v_pk_mul_f32 v[158:159], v[122:123], v[158:159]
	v_and_b32_e32 v161, 0xffff0000, v239
	v_pk_fma_f32 v[158:159], v[114:115], v[162:163], v[158:159]
	v_lshlrev_b32_e32 v162, 16, v170
	v_pk_fma_f32 v[158:159], v[110:111], v[160:161], v[158:159]
	v_and_b32_e32 v163, 0xffff0000, v170
	v_pk_add_f32 v[158:159], v[118:119], v[158:159]
	v_cvt_pk_bf16_f32 v148, v148, v149
	v_mul_f32_e32 v160, 0xbfb8aa3b, v158
	v_mul_f32_e32 v161, 0xbfb8aa3b, v159
	v_exp_f32_e32 v160, v160
	v_exp_f32_e32 v161, v161
	ds_bpermute_b32 v168, v225, v153
	ds_bpermute_b32 v169, v225, v154
	v_add_f32_e32 v160, 1.0, v160
	v_add_f32_e32 v161, 1.0, v161
	v_rcp_f32_e32 v160, v160
	v_rcp_f32_e32 v161, v161
	ds_bpermute_b32 v170, v225, v155
	v_pk_mul_f32 v[158:159], v[158:159], v[160:161]
	s_nop 0
	v_pk_mul_f32 v[150:151], v[150:151], v[158:159]
	v_lshlrev_b32_e32 v158, 16, v240
	v_and_b32_e32 v159, 0xffff0000, v240
	v_pk_mul_f32 v[158:159], v[100:101], v[158:159]
	v_lshlrev_b32_e32 v160, 16, v241
	v_and_b32_e32 v161, 0xffff0000, v241
	v_pk_fma_f32 v[158:159], v[92:93], v[162:163], v[158:159]
	v_lshlrev_b32_e32 v162, 16, v171
	v_pk_fma_f32 v[158:159], v[88:89], v[160:161], v[158:159]
	v_and_b32_e32 v163, 0xffff0000, v171
	v_pk_add_f32 v[158:159], v[96:97], v[158:159]
	v_cvt_pk_bf16_f32 v149, v150, v151
	v_mul_f32_e32 v160, 0xbfb8aa3b, v158
	v_mul_f32_e32 v161, 0xbfb8aa3b, v159
	v_exp_f32_e32 v160, v160
	v_exp_f32_e32 v161, v161
	v_add_f32_e32 v160, 1.0, v160
	v_add_f32_e32 v161, 1.0, v161
	v_rcp_f32_e32 v160, v160
	v_rcp_f32_e32 v161, v161
	s_nop 0
	v_pk_mul_f32 v[158:159], v[158:159], v[160:161]
	s_nop 0
	v_pk_mul_f32 v[144:145], v[144:145], v[158:159]
	v_lshlrev_b32_e32 v158, 16, v242
	v_and_b32_e32 v159, 0xffff0000, v242
	v_pk_mul_f32 v[158:159], v[102:103], v[158:159]
	v_lshlrev_b32_e32 v160, 16, v243
	v_and_b32_e32 v161, 0xffff0000, v243
	v_pk_fma_f32 v[158:159], v[94:95], v[162:163], v[158:159]
	ds_bpermute_b32 v163, v225, v152
	v_pk_fma_f32 v[158:159], v[90:91], v[160:161], v[158:159]
	v_cvt_pk_bf16_f32 v150, v144, v145
	v_pk_add_f32 v[158:159], v[98:99], v[158:159]
	v_mad_i64_i32 v[144:145], s[2:3], v233, s26, v[172:173]
	v_mul_f32_e32 v160, 0xbfb8aa3b, v158
	v_mul_f32_e32 v161, 0xbfb8aa3b, v159
	v_exp_f32_e32 v160, v160
	v_exp_f32_e32 v161, v161
	s_waitcnt lgkmcnt(1)
	v_cndmask_b32_e64 v233, v237, v170, s[6:7]
	v_or_b32_e32 v162, 32, v226
	v_add_f32_e32 v160, 1.0, v160
	v_add_f32_e32 v161, 1.0, v161
	v_rcp_f32_e32 v160, v160
	v_rcp_f32_e32 v161, v161
	s_nop 0
	v_pk_mul_f32 v[158:159], v[158:159], v[160:161]
	s_nop 0
	v_pk_mul_f32 v[146:147], v[146:147], v[158:159]
	ds_bpermute_b32 v158, v193, v164
	v_cvt_pk_bf16_f32 v151, v146, v147
	v_lshl_add_u64 v[146:147], v[144:145], 0, v[204:205]
	global_store_dwordx4 v[146:147], v[148:151], off
	ds_bpermute_b32 v159, v193, v165
	s_waitcnt lgkmcnt(1)
	v_cndmask_b32_e64 v145, v158, v174, s[4:5]
	v_lshlrev_b32_e32 v144, 16, v145
	v_and_b32_e32 v145, 0xffff0000, v145
	v_cndmask_b32_e64 v149, v234, v163, s[6:7]
	v_pk_mul_f32 v[144:145], v[120:121], v[144:145]
	v_lshlrev_b32_e32 v150, 16, v164
	v_and_b32_e32 v151, 0xffff0000, v164
	v_lshlrev_b32_e32 v148, 16, v149
	v_and_b32_e32 v149, 0xffff0000, v149
	v_pk_fma_f32 v[144:145], v[112:113], v[150:151], v[144:145]
	s_waitcnt lgkmcnt(0)
	v_cndmask_b32_e64 v171, v159, v175, s[4:5]
	v_pk_fma_f32 v[144:145], v[108:109], v[148:149], v[144:145]
	v_cndmask_b32_e64 v174, v235, v168, s[6:7]
	v_pk_add_f32 v[144:145], v[116:117], v[144:145]
	v_lshlrev_b32_e32 v150, 16, v165
	v_mul_f32_e32 v148, 0xbfb8aa3b, v144
	v_mul_f32_e32 v149, 0xbfb8aa3b, v145
	v_exp_f32_e32 v148, v148
	v_exp_f32_e32 v149, v149
	v_and_b32_e32 v151, 0xffff0000, v165
	ds_bpermute_b32 v160, v193, v166
	v_add_f32_e32 v148, 1.0, v148
	v_add_f32_e32 v149, 1.0, v149
	v_rcp_f32_e32 v148, v148
	v_rcp_f32_e32 v149, v149
	s_waitcnt lgkmcnt(0)
	v_cndmask_b32_e64 v175, v160, v231, s[4:5]
	v_cndmask_b32_e64 v231, v236, v169, s[6:7]
	ds_bpermute_b32 v161, v193, v167
	v_pk_mul_f32 v[144:145], v[144:145], v[148:149]
	v_lshlrev_b32_e32 v148, 16, v174
	v_pk_mul_f32 v[140:141], v[140:141], v[144:145]
	v_lshlrev_b32_e32 v144, 16, v171
	v_and_b32_e32 v145, 0xffff0000, v171
	v_pk_mul_f32 v[144:145], v[122:123], v[144:145]
	v_and_b32_e32 v149, 0xffff0000, v174
	v_pk_fma_f32 v[144:145], v[114:115], v[150:151], v[144:145]
	v_lshlrev_b32_e32 v150, 16, v166
	v_pk_fma_f32 v[144:145], v[110:111], v[148:149], v[144:145]
	v_and_b32_e32 v151, 0xffff0000, v166
	v_pk_add_f32 v[144:145], v[118:119], v[144:145]
	s_waitcnt lgkmcnt(0)
	v_cndmask_b32_e64 v232, v161, v232, s[4:5]
	v_mul_f32_e32 v148, 0xbfb8aa3b, v144
	v_mul_f32_e32 v149, 0xbfb8aa3b, v145
	v_exp_f32_e32 v148, v148
	v_exp_f32_e32 v149, v149
	v_or_b32_e32 v164, s12, v221
	v_add_f32_e32 v148, 1.0, v148
	v_add_f32_e32 v149, 1.0, v149
	v_rcp_f32_e32 v148, v148
	v_rcp_f32_e32 v149, v149
	s_nop 0
	v_pk_mul_f32 v[144:145], v[144:145], v[148:149]
	s_nop 0
	v_pk_mul_f32 v[142:143], v[142:143], v[144:145]
	v_lshlrev_b32_e32 v144, 16, v175
	v_and_b32_e32 v145, 0xffff0000, v175
	v_pk_mul_f32 v[144:145], v[100:101], v[144:145]
	v_lshlrev_b32_e32 v148, 16, v231
	v_and_b32_e32 v149, 0xffff0000, v231
	v_pk_fma_f32 v[144:145], v[92:93], v[150:151], v[144:145]
	v_lshlrev_b32_e32 v150, 16, v167
	v_pk_fma_f32 v[144:145], v[88:89], v[148:149], v[144:145]
	v_and_b32_e32 v151, 0xffff0000, v167
	v_pk_add_f32 v[144:145], v[96:97], v[144:145]
	s_nop 0
	v_mul_f32_e32 v148, 0xbfb8aa3b, v144
	v_mul_f32_e32 v149, 0xbfb8aa3b, v145
	v_exp_f32_e32 v148, v148
	v_exp_f32_e32 v149, v149
	v_add_f32_e32 v148, 1.0, v148
	v_add_f32_e32 v149, 1.0, v149
	v_rcp_f32_e32 v148, v148
	v_rcp_f32_e32 v149, v149
	s_nop 0
	v_pk_mul_f32 v[144:145], v[144:145], v[148:149]
	s_nop 0
	v_pk_mul_f32 v[144:145], v[136:137], v[144:145]
	v_lshlrev_b32_e32 v136, 16, v232
	v_and_b32_e32 v137, 0xffff0000, v232
	v_pk_mul_f32 v[136:137], v[102:103], v[136:137]
	v_lshlrev_b32_e32 v148, 16, v233
	v_and_b32_e32 v149, 0xffff0000, v233
	v_pk_fma_f32 v[136:137], v[94:95], v[150:151], v[136:137]
	v_cndmask_b32_e64 v150, v169, v228, s[6:7]
	v_pk_fma_f32 v[136:137], v[90:91], v[148:149], v[136:137]
	s_nop 0
	v_pk_add_f32 v[136:137], v[98:99], v[136:137]
	s_nop 0
	v_mul_f32_e32 v148, 0xbfb8aa3b, v136
	v_mul_f32_e32 v149, 0xbfb8aa3b, v137
	v_exp_f32_e32 v148, v148
	v_exp_f32_e32 v149, v149
	v_add_f32_e32 v148, 1.0, v148
	v_add_f32_e32 v149, 1.0, v149
	v_rcp_f32_e32 v148, v148
	v_rcp_f32_e32 v149, v149
	s_nop 0
	v_pk_mul_f32 v[136:137], v[136:137], v[148:149]
	s_nop 0
	v_pk_mul_f32 v[148:149], v[138:139], v[136:137]
	v_cvt_pk_bf16_f32 v136, v140, v141
	v_mad_i64_i32 v[140:141], s[2:3], v162, s26, v[172:173]
	v_cvt_pk_bf16_f32 v137, v142, v143
	v_cvt_pk_bf16_f32 v138, v144, v145
	v_cvt_pk_bf16_f32 v139, v148, v149
	v_lshl_add_u64 v[148:149], v[140:141], 0, v[204:205]
	global_store_dwordx4 v[148:149], v[136:139], off
	ds_bpermute_b32 v136, v193, v152
	ds_bpermute_b32 v137, v193, v153
	ds_bpermute_b32 v138, v193, v154
	ds_bpermute_b32 v139, v193, v155
	v_cndmask_b32_e64 v141, v163, v230, s[6:7]
	s_waitcnt lgkmcnt(3)
	v_cndmask_b32_e64 v140, v136, v158, s[4:5]
	s_waitcnt lgkmcnt(2)
	v_cndmask_b32_e64 v143, v137, v159, s[4:5]
	v_lshlrev_b32_e32 v136, 16, v140
	v_and_b32_e32 v137, 0xffff0000, v140
	s_waitcnt lgkmcnt(1)
	v_cndmask_b32_e64 v145, v138, v160, s[4:5]
	s_waitcnt lgkmcnt(0)
	v_cndmask_b32_e64 v151, v139, v161, s[4:5]
	v_lshlrev_b32_e32 v138, 16, v141
	v_and_b32_e32 v139, 0xffff0000, v141
	v_pk_mul_f32 v[136:137], v[120:121], v[136:137]
	v_lshlrev_b32_e32 v140, 16, v152
	v_and_b32_e32 v141, 0xffff0000, v152
	v_pk_fma_f32 v[136:137], v[112:113], v[140:141], v[136:137]
	v_cndmask_b32_e64 v144, v168, v229, s[6:7]
	v_pk_fma_f32 v[136:137], v[108:109], v[138:139], v[136:137]
	v_lshlrev_b32_e32 v140, 16, v153
	v_pk_add_f32 v[136:137], v[116:117], v[136:137]
	v_and_b32_e32 v141, 0xffff0000, v153
	v_mul_f32_e32 v138, 0xbfb8aa3b, v136
	v_mul_f32_e32 v139, 0xbfb8aa3b, v137
	v_exp_f32_e32 v138, v138
	v_exp_f32_e32 v139, v139
	v_cndmask_b32_e64 v158, v170, v227, s[6:7]
	v_or_b32_e32 v142, 48, v226
	v_add_f32_e32 v138, 1.0, v138
	v_add_f32_e32 v139, 1.0, v139
	v_rcp_f32_e32 v138, v138
	v_rcp_f32_e32 v139, v139
	s_nop 0
	v_pk_mul_f32 v[136:137], v[136:137], v[138:139]
	s_nop 0
	v_pk_mul_f32 v[132:133], v[132:133], v[136:137]
	v_lshlrev_b32_e32 v136, 16, v143
	v_and_b32_e32 v137, 0xffff0000, v143
	v_pk_mul_f32 v[136:137], v[122:123], v[136:137]
	v_lshlrev_b32_e32 v138, 16, v144
	v_and_b32_e32 v139, 0xffff0000, v144
	v_pk_fma_f32 v[136:137], v[114:115], v[140:141], v[136:137]
	v_lshlrev_b32_e32 v140, 16, v154
	v_pk_fma_f32 v[136:137], v[110:111], v[138:139], v[136:137]
	v_and_b32_e32 v141, 0xffff0000, v154
	v_pk_add_f32 v[136:137], v[118:119], v[136:137]
	s_nop 0
	v_mul_f32_e32 v138, 0xbfb8aa3b, v136
	v_mul_f32_e32 v139, 0xbfb8aa3b, v137
	v_exp_f32_e32 v138, v138
	v_exp_f32_e32 v139, v139
	v_add_f32_e32 v138, 1.0, v138
	v_add_f32_e32 v139, 1.0, v139
	v_rcp_f32_e32 v138, v138
	v_rcp_f32_e32 v139, v139
	s_nop 0
	v_pk_mul_f32 v[136:137], v[136:137], v[138:139]
	s_nop 0
	v_pk_mul_f32 v[134:135], v[134:135], v[136:137]
	v_lshlrev_b32_e32 v136, 16, v145
	v_and_b32_e32 v137, 0xffff0000, v145
	v_pk_mul_f32 v[136:137], v[100:101], v[136:137]
	v_lshlrev_b32_e32 v138, 16, v150
	v_and_b32_e32 v139, 0xffff0000, v150
	v_pk_fma_f32 v[136:137], v[92:93], v[140:141], v[136:137]
	v_lshlrev_b32_e32 v140, 16, v155
	v_pk_fma_f32 v[136:137], v[88:89], v[138:139], v[136:137]
	v_and_b32_e32 v141, 0xffff0000, v155
	v_pk_add_f32 v[136:137], v[96:97], v[136:137]
	s_nop 0
	v_mul_f32_e32 v138, 0xbfb8aa3b, v136
	v_mul_f32_e32 v139, 0xbfb8aa3b, v137
	v_exp_f32_e32 v138, v138
	v_exp_f32_e32 v139, v139
	v_add_f32_e32 v138, 1.0, v138
	v_add_f32_e32 v139, 1.0, v139
	v_rcp_f32_e32 v138, v138
	v_rcp_f32_e32 v139, v139
	s_nop 0
	v_pk_mul_f32 v[136:137], v[136:137], v[138:139]
	s_nop 0
	v_pk_mul_f32 v[136:137], v[128:129], v[136:137]
	v_lshlrev_b32_e32 v128, 16, v151
	v_and_b32_e32 v129, 0xffff0000, v151
	v_pk_mul_f32 v[128:129], v[102:103], v[128:129]
	v_lshlrev_b32_e32 v138, 16, v158
	v_and_b32_e32 v139, 0xffff0000, v158
	v_pk_fma_f32 v[128:129], v[94:95], v[140:141], v[128:129]
	s_nop 0
	v_pk_fma_f32 v[128:129], v[90:91], v[138:139], v[128:129]
	s_nop 0
	v_pk_add_f32 v[128:129], v[98:99], v[128:129]
	s_nop 0
	v_mul_f32_e32 v138, 0xbfb8aa3b, v128
	v_mul_f32_e32 v139, 0xbfb8aa3b, v129
	v_exp_f32_e32 v138, v138
	v_exp_f32_e32 v139, v139
	v_add_f32_e32 v138, 1.0, v138
	v_add_f32_e32 v139, 1.0, v139
	v_rcp_f32_e32 v138, v138
	v_rcp_f32_e32 v139, v139
	s_nop 0
	v_pk_mul_f32 v[128:129], v[128:129], v[138:139]
	s_nop 0
	v_pk_mul_f32 v[138:139], v[130:131], v[128:129]
	v_cvt_pk_bf16_f32 v128, v132, v133
	v_mad_i64_i32 v[132:133], s[2:3], v142, s26, v[172:173]
	v_cvt_pk_bf16_f32 v129, v134, v135
	v_cvt_pk_bf16_f32 v130, v136, v137
	v_cvt_pk_bf16_f32 v131, v138, v139
	v_lshl_add_u64 v[144:145], v[132:133], 0, v[204:205]
	global_store_dwordx4 v[144:145], v[128:131], off
	s_nop 0
	s_nop 0
	s_nop 1
	v_mad_i64_i32 v[128:129], s[2:3], v164, s26, v[208:209]
	v_lshl_add_u64 v[150:151], v[128:129], 0, v[204:205]
	v_add_co_u32_e32 v152, vcc, s21, v150
	s_mul_hi_i32 s2, s12, 0x2c00
	s_nop 0
	v_addc_co_u32_e32 v153, vcc, 0, v151, vcc
	v_add_co_u32_e32 v154, vcc, s22, v150
	global_load_dwordx4 v[140:143], v[150:151], off
	global_load_dwordx4 v[136:139], v[152:153], off
	v_addc_co_u32_e32 v155, vcc, 0, v151, vcc
	v_add_co_u32_e32 v158, vcc, s23, v150
	s_cselect_b64 s[22:23], -1, 0
	s_add_i32 s1, s1, 0x160000
	s_add_u32 s0, s10, s1
	s_addc_u32 s1, s11, s2
	s_and_b64 s[2:3], s[22:23], exec
	v_addc_co_u32_e32 v159, vcc, 0, v151, vcc
	s_cselect_b32 s2, 0, 0xffffd400
	s_cselect_b32 s3, 0, -1
	s_cmp_eq_u32 s15, s13
	s_cselect_b64 vcc, -1, 0
	v_lshl_add_u64 v[160:161], s[0:1], 0, v[204:205]
	s_and_b64 s[0:1], vcc, exec
	s_cselect_b32 s72, 0, 0xb0000
	v_lshl_add_u64 v[162:163], v[160:161], 0, s[2:3]
	v_lshl_add_u64 v[160:161], v[160:161], 0, s[72:73]
	global_load_dwordx4 v[166:169], v[162:163], off
	global_load_dwordx4 v[226:229], v[160:161], off
	global_load_dwordx4 v[132:135], v[154:155], off
	global_load_dwordx4 v[128:131], v[158:159], off
	s_waitcnt vmcnt(5)
	ds_bpermute_b32 v175, v225, v140
	ds_bpermute_b32 v208, v225, v141
	ds_bpermute_b32 v209, v225, v142
	s_waitcnt vmcnt(4)
	ds_bpermute_b32 v231, v225, v136
	ds_bpermute_b32 v232, v225, v137
	ds_bpermute_b32 v233, v225, v138
	ds_bpermute_b32 v230, v225, v143
	ds_bpermute_b32 v234, v225, v139
	s_waitcnt lgkmcnt(4)
	v_cndmask_b32_e64 v175, v175, v231, s[6:7]
	s_waitcnt lgkmcnt(3)
	v_cndmask_b32_e64 v237, v208, v232, s[6:7]
	s_waitcnt lgkmcnt(2)
	v_cndmask_b32_e64 v239, v209, v233, s[6:7]
	v_lshlrev_b32_e32 v208, 16, v140
	v_and_b32_e32 v209, 0xffff0000, v140
	s_waitcnt lgkmcnt(0)
	v_cndmask_b32_e64 v230, v230, v234, s[6:7]
	s_waitcnt vmcnt(3)
	v_cndmask_b32_e64 v170, v168, 0, s[22:23]
	s_waitcnt vmcnt(2)
	v_cndmask_b32_e64 v168, v226, 0, vcc
	ds_bpermute_b32 v226, v193, v140
	v_cndmask_b32_e64 v171, v167, 0, s[22:23]
	v_cndmask_b32_e64 v174, v166, 0, s[22:23]
	v_cndmask_b32_e64 v166, v228, 0, vcc
	v_cndmask_b32_e64 v167, v227, 0, vcc
	ds_bpermute_b32 v227, v193, v141
	ds_bpermute_b32 v228, v193, v142
	s_waitcnt lgkmcnt(2)
	v_cndmask_b32_e64 v235, v226, v174, s[4:5]
	v_lshlrev_b32_e32 v174, 16, v175
	v_and_b32_e32 v175, 0xffff0000, v175
	s_waitcnt lgkmcnt(1)
	v_cndmask_b32_e64 v236, v227, v171, s[4:5]
	s_waitcnt lgkmcnt(0)
	v_cndmask_b32_e64 v238, v228, v170, s[4:5]
	v_lshlrev_b32_e32 v170, 16, v235
	v_and_b32_e32 v171, 0xffff0000, v235
	v_pk_mul_f32 v[170:171], v[120:121], v[170:171]
	v_cndmask_b32_e64 v165, v229, 0, vcc
	v_pk_fma_f32 v[170:171], v[112:113], v[208:209], v[170:171]
	ds_bpermute_b32 v229, v193, v143
	v_pk_fma_f32 v[170:171], v[108:109], v[174:175], v[170:171]
	v_cndmask_b32_e64 v169, v169, 0, s[22:23]
	v_pk_add_f32 v[170:171], v[116:117], v[170:171]
	s_waitcnt lgkmcnt(0)
	v_cndmask_b32_e64 v169, v229, v169, s[4:5]
	v_mul_f32_e32 v140, 0xbfb8aa3b, v170
	v_exp_f32_e32 v140, v140
	s_nop 0
	v_add_f32_e32 v140, 1.0, v140
	v_rcp_f32_e32 v174, v140
	v_mul_f32_e32 v140, 0xbfb8aa3b, v171
	v_exp_f32_e32 v140, v140
	s_nop 0
	v_add_f32_e32 v140, 1.0, v140
	v_rcp_f32_e32 v175, v140
	v_lshlrev_b32_e32 v140, 16, v141
	v_and_b32_e32 v141, 0xffff0000, v141
	v_pk_mul_f32 v[170:171], v[170:171], v[174:175]
	s_nop 0
	v_pk_mul_f32 v[124:125], v[124:125], v[170:171]
	v_lshlrev_b32_e32 v170, 16, v236
	v_and_b32_e32 v171, 0xffff0000, v236
	v_pk_mul_f32 v[170:171], v[122:123], v[170:171]
	v_lshlrev_b32_e32 v174, 16, v237
	v_and_b32_e32 v175, 0xffff0000, v237
	v_pk_fma_f32 v[140:141], v[114:115], v[140:141], v[170:171]
	s_nop 0
	v_pk_fma_f32 v[140:141], v[110:111], v[174:175], v[140:141]
	v_lshlrev_b32_e32 v174, 16, v142
	v_pk_add_f32 v[140:141], v[118:119], v[140:141]
	v_and_b32_e32 v175, 0xffff0000, v142
	v_mul_f32_e32 v170, 0xbfb8aa3b, v140
	v_mul_f32_e32 v171, 0xbfb8aa3b, v141
	v_exp_f32_e32 v170, v170
	v_exp_f32_e32 v171, v171
	v_add_f32_e32 v170, 1.0, v170
	v_add_f32_e32 v171, 1.0, v171
	v_rcp_f32_e32 v170, v170
	v_rcp_f32_e32 v171, v171
	s_nop 0
	v_pk_mul_f32 v[140:141], v[140:141], v[170:171]
	s_nop 0
	v_pk_mul_f32 v[126:127], v[126:127], v[140:141]
	v_lshlrev_b32_e32 v140, 16, v238
	v_and_b32_e32 v141, 0xffff0000, v238
	v_pk_mul_f32 v[140:141], v[100:101], v[140:141]
	v_lshlrev_b32_e32 v170, 16, v239
	v_and_b32_e32 v171, 0xffff0000, v239
	v_pk_fma_f32 v[140:141], v[92:93], v[174:175], v[140:141]
	s_waitcnt vmcnt(1)
	ds_bpermute_b32 v174, v225, v134
	v_pk_fma_f32 v[140:141], v[88:89], v[170:171], v[140:141]
	ds_bpermute_b32 v175, v225, v135
	v_pk_add_f32 v[140:141], v[96:97], v[140:141]
	s_nop 0
	v_mul_f32_e32 v142, 0xbfb8aa3b, v140
	v_exp_f32_e32 v142, v142
	s_nop 0
	v_add_f32_e32 v142, 1.0, v142
	v_rcp_f32_e32 v170, v142
	v_mul_f32_e32 v142, 0xbfb8aa3b, v141
	v_exp_f32_e32 v142, v142
	s_nop 0
	v_add_f32_e32 v142, 1.0, v142
	v_rcp_f32_e32 v171, v142
	v_lshlrev_b32_e32 v142, 16, v143
	v_and_b32_e32 v143, 0xffff0000, v143
	v_pk_mul_f32 v[140:141], v[140:141], v[170:171]
	s_nop 0
	v_pk_mul_f32 v[140:141], v[104:105], v[140:141]
	v_lshlrev_b32_e32 v104, 16, v169
	v_and_b32_e32 v105, 0xffff0000, v169
	v_pk_mul_f32 v[104:105], v[102:103], v[104:105]
	v_lshlrev_b32_e32 v170, 16, v230
	v_and_b32_e32 v171, 0xffff0000, v230
	v_pk_fma_f32 v[104:105], v[94:95], v[142:143], v[104:105]
	v_or_b32_e32 v169, 16, v164
	v_pk_fma_f32 v[104:105], v[90:91], v[170:171], v[104:105]
	ds_bpermute_b32 v170, v225, v132
	v_pk_add_f32 v[104:105], v[98:99], v[104:105]
	ds_bpermute_b32 v171, v225, v133
	v_mul_f32_e32 v142, 0xbfb8aa3b, v104
	v_mul_f32_e32 v143, 0xbfb8aa3b, v105
	v_exp_f32_e32 v142, v142
	v_exp_f32_e32 v143, v143
	s_waitcnt lgkmcnt(0)
	v_cndmask_b32_e64 v209, v232, v171, s[6:7]
	v_add_f32_e32 v142, 1.0, v142
	v_add_f32_e32 v143, 1.0, v143
	v_rcp_f32_e32 v142, v142
	v_rcp_f32_e32 v143, v143
	s_nop 0
	v_pk_mul_f32 v[104:105], v[104:105], v[142:143]
	s_nop 0
	v_pk_mul_f32 v[142:143], v[106:107], v[104:105]
	v_cvt_pk_bf16_f32 v106, v140, v141
	ds_bpermute_b32 v140, v193, v136
	v_cvt_pk_bf16_f32 v104, v124, v125
	v_mad_i64_i32 v[124:125], s[0:1], v164, s26, v[172:173]
	v_cvt_pk_bf16_f32 v105, v126, v127
	v_cvt_pk_bf16_f32 v107, v142, v143
	v_lshl_add_u64 v[124:125], v[124:125], 0, v[204:205]
	global_store_dwordx4 v[124:125], v[104:107], off
	v_lshlrev_b32_e32 v126, 16, v136
	v_and_b32_e32 v127, 0xffff0000, v136
	s_waitcnt lgkmcnt(0)
	v_cndmask_b32_e64 v105, v140, v226, s[4:5]
	v_lshlrev_b32_e32 v104, 16, v105
	v_and_b32_e32 v105, 0xffff0000, v105
	v_cndmask_b32_e64 v107, v231, v170, s[6:7]
	v_pk_mul_f32 v[104:105], v[120:121], v[104:105]
	v_lshlrev_b32_e32 v106, 16, v107
	v_and_b32_e32 v107, 0xffff0000, v107
	v_pk_fma_f32 v[104:105], v[112:113], v[126:127], v[104:105]
	ds_bpermute_b32 v141, v193, v137
	v_pk_fma_f32 v[104:105], v[108:109], v[106:107], v[104:105]
	v_lshlrev_b32_e32 v126, 16, v137
	v_pk_add_f32 v[104:105], v[116:117], v[104:105]
	v_and_b32_e32 v127, 0xffff0000, v137
	v_mul_f32_e32 v106, 0xbfb8aa3b, v104
	v_mul_f32_e32 v107, 0xbfb8aa3b, v105
	v_exp_f32_e32 v106, v106
	v_exp_f32_e32 v107, v107
	s_waitcnt lgkmcnt(0)
	v_cndmask_b32_e64 v208, v141, v227, s[4:5]
	ds_bpermute_b32 v142, v193, v138
	v_add_f32_e32 v106, 1.0, v106
	v_add_f32_e32 v107, 1.0, v107
	v_rcp_f32_e32 v106, v106
	v_rcp_f32_e32 v107, v107
	s_waitcnt lgkmcnt(0)
	v_cndmask_b32_e64 v226, v142, v228, s[4:5]
	v_cndmask_b32_e64 v227, v233, v174, s[6:7]
	ds_bpermute_b32 v143, v193, v139
	v_pk_mul_f32 v[104:105], v[104:105], v[106:107]
	v_lshlrev_b32_e32 v106, 16, v209
	v_pk_mul_f32 v[84:85], v[84:85], v[104:105]
	v_lshlrev_b32_e32 v104, 16, v208
	v_and_b32_e32 v105, 0xffff0000, v208
	v_pk_mul_f32 v[104:105], v[122:123], v[104:105]
	v_and_b32_e32 v107, 0xffff0000, v209
	v_pk_fma_f32 v[104:105], v[114:115], v[126:127], v[104:105]
	v_lshlrev_b32_e32 v126, 16, v138
	v_pk_fma_f32 v[104:105], v[110:111], v[106:107], v[104:105]
	v_and_b32_e32 v127, 0xffff0000, v138
	v_pk_add_f32 v[104:105], v[118:119], v[104:105]
	s_waitcnt lgkmcnt(0)
	v_cndmask_b32_e64 v228, v143, v229, s[4:5]
	v_mul_f32_e32 v106, 0xbfb8aa3b, v104
	v_mul_f32_e32 v107, 0xbfb8aa3b, v105
	v_exp_f32_e32 v106, v106
	v_exp_f32_e32 v107, v107
	v_cndmask_b32_e64 v229, v234, v175, s[6:7]
	s_waitcnt vmcnt(1)
	ds_bpermute_b32 v136, v225, v129
	v_add_f32_e32 v106, 1.0, v106
	v_add_f32_e32 v107, 1.0, v107
	v_rcp_f32_e32 v106, v106
	v_rcp_f32_e32 v107, v107
	ds_bpermute_b32 v137, v225, v130
	ds_bpermute_b32 v138, v225, v131
	v_pk_mul_f32 v[104:105], v[104:105], v[106:107]
	s_nop 0
	v_pk_mul_f32 v[86:87], v[86:87], v[104:105]
	v_lshlrev_b32_e32 v104, 16, v226
	v_and_b32_e32 v105, 0xffff0000, v226
	v_pk_mul_f32 v[104:105], v[100:101], v[104:105]
	v_lshlrev_b32_e32 v106, 16, v227
	v_and_b32_e32 v107, 0xffff0000, v227
	v_pk_fma_f32 v[104:105], v[92:93], v[126:127], v[104:105]
	v_lshlrev_b32_e32 v126, 16, v139
	v_pk_fma_f32 v[104:105], v[88:89], v[106:107], v[104:105]
	v_and_b32_e32 v127, 0xffff0000, v139
	v_pk_add_f32 v[104:105], v[96:97], v[104:105]
	s_nop 0
	v_mul_f32_e32 v106, 0xbfb8aa3b, v104
	v_mul_f32_e32 v107, 0xbfb8aa3b, v105
	v_exp_f32_e32 v106, v106
	v_exp_f32_e32 v107, v107
	v_add_f32_e32 v106, 1.0, v106
	v_add_f32_e32 v107, 1.0, v107
	v_rcp_f32_e32 v106, v106
	v_rcp_f32_e32 v107, v107
	s_nop 0
	v_pk_mul_f32 v[104:105], v[104:105], v[106:107]
	s_nop 0
	v_pk_mul_f32 v[104:105], v[80:81], v[104:105]
	v_lshlrev_b32_e32 v80, 16, v228
	v_and_b32_e32 v81, 0xffff0000, v228
	v_pk_mul_f32 v[80:81], v[102:103], v[80:81]
	v_lshlrev_b32_e32 v106, 16, v229
	v_and_b32_e32 v107, 0xffff0000, v229
	v_pk_fma_f32 v[80:81], v[94:95], v[126:127], v[80:81]
	s_nop 0
	v_pk_fma_f32 v[80:81], v[90:91], v[106:107], v[80:81]
	s_nop 0
	v_pk_add_f32 v[80:81], v[98:99], v[80:81]
	s_nop 0
	v_mul_f32_e32 v106, 0xbfb8aa3b, v80
	v_mul_f32_e32 v107, 0xbfb8aa3b, v81
	v_exp_f32_e32 v106, v106
	v_exp_f32_e32 v107, v107
	v_add_f32_e32 v106, 1.0, v106
	v_add_f32_e32 v107, 1.0, v107
	v_rcp_f32_e32 v106, v106
	v_rcp_f32_e32 v107, v107
	s_nop 0
	v_pk_mul_f32 v[80:81], v[80:81], v[106:107]
	s_nop 0
	v_pk_mul_f32 v[106:107], v[82:83], v[80:81]
	v_cvt_pk_bf16_f32 v81, v86, v87
	ds_bpermute_b32 v86, v193, v132
	v_cvt_pk_bf16_f32 v83, v106, v107
	ds_bpermute_b32 v107, v225, v128
	v_cvt_pk_bf16_f32 v80, v84, v85
	v_mad_i64_i32 v[84:85], s[0:1], v169, s26, v[172:173]
	v_cvt_pk_bf16_f32 v82, v104, v105
	v_lshl_add_u64 v[126:127], v[84:85], 0, v[204:205]
	global_store_dwordx4 v[126:127], v[80:83], off
	v_lshlrev_b32_e32 v84, 16, v132
	v_and_b32_e32 v85, 0xffff0000, v132
	s_waitcnt lgkmcnt(1)
	v_cndmask_b32_e64 v81, v86, v140, s[4:5]
	v_lshlrev_b32_e32 v80, 16, v81
	v_and_b32_e32 v81, 0xffff0000, v81
	s_waitcnt lgkmcnt(0)
	v_cndmask_b32_e64 v83, v170, v107, s[6:7]
	v_pk_mul_f32 v[80:81], v[120:121], v[80:81]
	v_lshlrev_b32_e32 v82, 16, v83
	v_and_b32_e32 v83, 0xffff0000, v83
	v_pk_fma_f32 v[80:81], v[112:113], v[84:85], v[80:81]
	ds_bpermute_b32 v87, v193, v133
	v_pk_fma_f32 v[80:81], v[108:109], v[82:83], v[80:81]
	v_cndmask_b32_e64 v140, v171, v136, s[6:7]
	v_pk_add_f32 v[80:81], v[116:117], v[80:81]
	v_lshlrev_b32_e32 v84, 16, v133
	v_mul_f32_e32 v82, 0xbfb8aa3b, v80
	v_mul_f32_e32 v83, 0xbfb8aa3b, v81
	v_exp_f32_e32 v82, v82
	v_exp_f32_e32 v83, v83
	s_waitcnt lgkmcnt(0)
	v_cndmask_b32_e64 v139, v87, v141, s[4:5]
	v_and_b32_e32 v85, 0xffff0000, v133
	v_add_f32_e32 v82, 1.0, v82
	v_add_f32_e32 v83, 1.0, v83
	v_rcp_f32_e32 v82, v82
	v_rcp_f32_e32 v83, v83
	ds_bpermute_b32 v104, v193, v134
	ds_bpermute_b32 v105, v193, v135
	v_cndmask_b32_e64 v169, v175, v138, s[6:7]
	v_pk_mul_f32 v[80:81], v[80:81], v[82:83]
	v_lshlrev_b32_e32 v82, 16, v140
	v_pk_mul_f32 v[76:77], v[76:77], v[80:81]
	v_lshlrev_b32_e32 v80, 16, v139
	v_and_b32_e32 v81, 0xffff0000, v139
	v_pk_mul_f32 v[80:81], v[122:123], v[80:81]
	v_and_b32_e32 v83, 0xffff0000, v140
	v_pk_fma_f32 v[80:81], v[114:115], v[84:85], v[80:81]
	s_waitcnt lgkmcnt(1)
	v_cndmask_b32_e64 v141, v104, v142, s[4:5]
	v_pk_fma_f32 v[80:81], v[110:111], v[82:83], v[80:81]
	v_cndmask_b32_e64 v142, v174, v137, s[6:7]
	v_pk_add_f32 v[80:81], v[118:119], v[80:81]
	v_lshlrev_b32_e32 v84, 16, v134
	v_mul_f32_e32 v82, 0xbfb8aa3b, v80
	v_mul_f32_e32 v83, 0xbfb8aa3b, v81
	v_exp_f32_e32 v82, v82
	v_exp_f32_e32 v83, v83
	v_and_b32_e32 v85, 0xffff0000, v134
	s_waitcnt lgkmcnt(0)
	v_cndmask_b32_e64 v143, v105, v143, s[4:5]
	v_add_f32_e32 v82, 1.0, v82
	v_add_f32_e32 v83, 1.0, v83
	v_rcp_f32_e32 v82, v82
	v_rcp_f32_e32 v83, v83
	v_or_b32_e32 v106, 32, v164
	v_pk_mul_f32 v[80:81], v[80:81], v[82:83]
	s_nop 0
	v_pk_mul_f32 v[78:79], v[78:79], v[80:81]
	v_lshlrev_b32_e32 v80, 16, v141
	v_and_b32_e32 v81, 0xffff0000, v141
	v_pk_mul_f32 v[80:81], v[100:101], v[80:81]
	v_lshlrev_b32_e32 v82, 16, v142
	v_and_b32_e32 v83, 0xffff0000, v142
	v_pk_fma_f32 v[80:81], v[92:93], v[84:85], v[80:81]
	v_lshlrev_b32_e32 v84, 16, v135
	v_pk_fma_f32 v[80:81], v[88:89], v[82:83], v[80:81]
	v_and_b32_e32 v85, 0xffff0000, v135
	v_pk_add_f32 v[80:81], v[96:97], v[80:81]
	s_nop 0
	v_mul_f32_e32 v82, 0xbfb8aa3b, v80
	v_mul_f32_e32 v83, 0xbfb8aa3b, v81
	v_exp_f32_e32 v82, v82
	v_exp_f32_e32 v83, v83
	v_add_f32_e32 v82, 1.0, v82
	v_add_f32_e32 v83, 1.0, v83
	v_rcp_f32_e32 v82, v82
	v_rcp_f32_e32 v83, v83
	s_nop 0
	v_pk_mul_f32 v[80:81], v[80:81], v[82:83]
	s_nop 0
	v_pk_mul_f32 v[80:81], v[72:73], v[80:81]
	v_lshlrev_b32_e32 v72, 16, v143
	v_and_b32_e32 v73, 0xffff0000, v143
	v_pk_mul_f32 v[72:73], v[102:103], v[72:73]
	v_lshlrev_b32_e32 v82, 16, v169
	v_and_b32_e32 v83, 0xffff0000, v169
	v_pk_fma_f32 v[72:73], v[94:95], v[84:85], v[72:73]
	v_cndmask_b32_e64 v84, v138, v165, s[6:7]
	v_pk_fma_f32 v[72:73], v[90:91], v[82:83], v[72:73]
	s_nop 0
	v_pk_add_f32 v[72:73], v[98:99], v[72:73]
	s_nop 0
	v_mul_f32_e32 v82, 0xbfb8aa3b, v72
	v_mul_f32_e32 v83, 0xbfb8aa3b, v73
	v_exp_f32_e32 v82, v82
	v_exp_f32_e32 v83, v83
	v_add_f32_e32 v82, 1.0, v82
	v_add_f32_e32 v83, 1.0, v83
	v_rcp_f32_e32 v82, v82
	v_rcp_f32_e32 v83, v83
	s_nop 0
	v_pk_mul_f32 v[72:73], v[72:73], v[82:83]
	s_nop 0
	v_pk_mul_f32 v[82:83], v[74:75], v[72:73]
	v_cvt_pk_bf16_f32 v72, v76, v77
	v_mad_i64_i32 v[76:77], s[0:1], v106, s26, v[172:173]
	v_cvt_pk_bf16_f32 v73, v78, v79
	v_cvt_pk_bf16_f32 v74, v80, v81
	v_cvt_pk_bf16_f32 v75, v82, v83
	v_lshl_add_u64 v[132:133], v[76:77], 0, v[204:205]
	global_store_dwordx4 v[132:133], v[72:75], off
	ds_bpermute_b32 v72, v193, v128
	ds_bpermute_b32 v73, v193, v129
	ds_bpermute_b32 v74, v193, v130
	ds_bpermute_b32 v75, v193, v131
	v_cndmask_b32_e64 v77, v107, v168, s[6:7]
	s_waitcnt lgkmcnt(3)
	v_cndmask_b32_e64 v76, v72, v86, s[4:5]
	s_waitcnt lgkmcnt(2)
	v_cndmask_b32_e64 v79, v73, v87, s[4:5]
	v_lshlrev_b32_e32 v72, 16, v76
	v_and_b32_e32 v73, 0xffff0000, v76
	s_waitcnt lgkmcnt(1)
	v_cndmask_b32_e64 v81, v74, v104, s[4:5]
	s_waitcnt lgkmcnt(0)
	v_cndmask_b32_e64 v83, v75, v105, s[4:5]
	v_lshlrev_b32_e32 v74, 16, v77
	v_and_b32_e32 v75, 0xffff0000, v77
	v_pk_mul_f32 v[72:73], v[120:121], v[72:73]
	v_lshlrev_b32_e32 v76, 16, v128
	v_and_b32_e32 v77, 0xffff0000, v128
	v_pk_fma_f32 v[72:73], v[112:113], v[76:77], v[72:73]
	v_cndmask_b32_e64 v80, v136, v167, s[6:7]
	v_pk_fma_f32 v[72:73], v[108:109], v[74:75], v[72:73]
	v_lshlrev_b32_e32 v76, 16, v129
	v_pk_add_f32 v[72:73], v[116:117], v[72:73]
	v_and_b32_e32 v77, 0xffff0000, v129
	v_mul_f32_e32 v74, 0xbfb8aa3b, v72
	v_mul_f32_e32 v75, 0xbfb8aa3b, v73
	v_exp_f32_e32 v74, v74
	v_exp_f32_e32 v75, v75
	v_cndmask_b32_e64 v82, v137, v166, s[6:7]
	v_or_b32_e32 v78, 48, v164
	v_add_f32_e32 v74, 1.0, v74
	v_add_f32_e32 v75, 1.0, v75
	v_rcp_f32_e32 v74, v74
	v_rcp_f32_e32 v75, v75
	s_nop 0
	v_pk_mul_f32 v[72:73], v[72:73], v[74:75]
	s_nop 0
	v_pk_mul_f32 v[68:69], v[68:69], v[72:73]
	v_lshlrev_b32_e32 v72, 16, v79
	v_and_b32_e32 v73, 0xffff0000, v79
	v_pk_mul_f32 v[72:73], v[122:123], v[72:73]
	v_lshlrev_b32_e32 v74, 16, v80
	v_and_b32_e32 v75, 0xffff0000, v80
	v_pk_fma_f32 v[72:73], v[114:115], v[76:77], v[72:73]
	v_lshlrev_b32_e32 v76, 16, v130
	v_pk_fma_f32 v[72:73], v[110:111], v[74:75], v[72:73]
	v_and_b32_e32 v77, 0xffff0000, v130
	v_pk_add_f32 v[72:73], v[118:119], v[72:73]
	s_nop 0
	v_mul_f32_e32 v74, 0xbfb8aa3b, v72
	v_mul_f32_e32 v75, 0xbfb8aa3b, v73
	v_exp_f32_e32 v74, v74
	v_exp_f32_e32 v75, v75
	v_add_f32_e32 v74, 1.0, v74
	v_add_f32_e32 v75, 1.0, v75
	v_rcp_f32_e32 v74, v74
	v_rcp_f32_e32 v75, v75
	s_nop 0
	v_pk_mul_f32 v[72:73], v[72:73], v[74:75]
	s_nop 0
	v_pk_mul_f32 v[70:71], v[70:71], v[72:73]
	v_lshlrev_b32_e32 v72, 16, v81
	v_and_b32_e32 v73, 0xffff0000, v81
	v_pk_mul_f32 v[72:73], v[100:101], v[72:73]
	v_lshlrev_b32_e32 v74, 16, v82
	v_and_b32_e32 v75, 0xffff0000, v82
	v_pk_fma_f32 v[72:73], v[92:93], v[76:77], v[72:73]
	v_lshlrev_b32_e32 v76, 16, v131
	v_pk_fma_f32 v[72:73], v[88:89], v[74:75], v[72:73]
	v_and_b32_e32 v77, 0xffff0000, v131
	v_pk_add_f32 v[72:73], v[96:97], v[72:73]
	s_nop 0
	v_mul_f32_e32 v74, 0xbfb8aa3b, v72
	v_mul_f32_e32 v75, 0xbfb8aa3b, v73
	v_exp_f32_e32 v74, v74
	v_exp_f32_e32 v75, v75
	v_add_f32_e32 v74, 1.0, v74
	v_add_f32_e32 v75, 1.0, v75
	v_rcp_f32_e32 v74, v74
	v_rcp_f32_e32 v75, v75
	s_nop 0
	v_pk_mul_f32 v[72:73], v[72:73], v[74:75]
	s_nop 0
	v_pk_mul_f32 v[72:73], v[64:65], v[72:73]
	v_lshlrev_b32_e32 v64, 16, v83
	v_and_b32_e32 v65, 0xffff0000, v83
	v_pk_mul_f32 v[64:65], v[102:103], v[64:65]
	v_lshlrev_b32_e32 v74, 16, v84
	v_and_b32_e32 v75, 0xffff0000, v84
	v_pk_fma_f32 v[64:65], v[94:95], v[76:77], v[64:65]
	s_nop 0
	v_pk_fma_f32 v[64:65], v[90:91], v[74:75], v[64:65]
	s_nop 0
	v_pk_add_f32 v[64:65], v[98:99], v[64:65]
	s_nop 0
	v_mul_f32_e32 v74, 0xbfb8aa3b, v64
	v_mul_f32_e32 v75, 0xbfb8aa3b, v65
	v_exp_f32_e32 v74, v74
	v_exp_f32_e32 v75, v75
	v_add_f32_e32 v74, 1.0, v74
	v_add_f32_e32 v75, 1.0, v75
	v_rcp_f32_e32 v74, v74
	v_rcp_f32_e32 v75, v75
	s_nop 0
	v_pk_mul_f32 v[64:65], v[64:65], v[74:75]
	s_nop 0
	v_pk_mul_f32 v[74:75], v[66:67], v[64:65]
	v_cvt_pk_bf16_f32 v64, v68, v69
	v_mad_i64_i32 v[68:69], s[0:1], v78, s26, v[172:173]
	v_cvt_pk_bf16_f32 v65, v70, v71
	v_cvt_pk_bf16_f32 v66, v72, v73
	v_cvt_pk_bf16_f32 v67, v74, v75
	v_lshl_add_u64 v[112:113], v[68:69], 0, v[204:205]
	global_store_dwordx4 v[112:113], v[64:67], off
	s_mov_b64 s[0:1], -1
	s_nop 0
	v_or_b32_e32 v64, 0x80, v192
	v_ashrrev_i32_e32 v65, 31, v64
	v_lshlrev_b64 v[64:65], 2, v[64:65]
	v_lshl_add_u64 v[66:67], s[46:47], 0, v[64:65]
	v_lshl_add_u64 v[72:73], s[48:49], 0, v[64:65]
	global_load_dwordx4 v[76:79], v[190:191], off offset:528
	global_load_dwordx4 v[92:95], v[190:191], off offset:512
	global_load_dwordx4 v[68:71], v[66:67], off offset:16
	global_load_dwordx4 v[84:87], v[66:67], off
	s_nop 0
	global_load_dwordx4 v[64:67], v[72:73], off offset:16
	global_load_dwordx4 v[80:83], v[72:73], off
	s_nop 0
	global_load_dwordx4 v[72:75], v[188:189], off offset:528
	global_load_dwordx4 v[88:91], v[188:189], off offset:512
	global_load_dwordx4 v[108:111], v[194:195], off offset:256
	global_load_dwordx4 v[104:107], v[198:199], off offset:256
	global_load_dwordx4 v[100:103], v[200:201], off offset:256
	global_load_dwordx4 v[96:99], v[206:207], off offset:256
	global_load_dwordx4 v[114:117], v[196:197], off offset:256
	global_load_dwordx4 v[118:121], v[202:203], off offset:256
	s_waitcnt vmcnt(5)
	ds_bpermute_b32 v130, v193, v108
	s_waitcnt vmcnt(4)
	ds_bpermute_b32 v136, v225, v104
	ds_bpermute_b32 v137, v225, v105
	ds_bpermute_b32 v134, v193, v110
	s_waitcnt vmcnt(1)
	v_cndmask_b32_e64 v122, v117, 0, s[62:63]
	v_cndmask_b32_e64 v123, v116, 0, s[62:63]
	s_waitcnt vmcnt(0)
	v_cndmask_b32_e64 v116, v119, 0, s[50:51]
	v_cndmask_b32_e64 v117, v118, 0, s[50:51]
	ds_bpermute_b32 v118, v225, v108
	ds_bpermute_b32 v119, v225, v109
	ds_bpermute_b32 v135, v193, v111
	v_cndmask_b32_e64 v128, v115, 0, s[62:63]
	v_cndmask_b32_e64 v129, v114, 0, s[62:63]
	v_cndmask_b32_e64 v114, v121, 0, s[50:51]
	v_cndmask_b32_e64 v115, v120, 0, s[50:51]
	ds_bpermute_b32 v120, v225, v110
	ds_bpermute_b32 v121, v225, v111
	ds_bpermute_b32 v138, v225, v106
	ds_bpermute_b32 v139, v225, v107
	s_waitcnt lgkmcnt(10)
	v_cndmask_b32_e64 v129, v130, v129, s[4:5]
	s_waitcnt lgkmcnt(6)
	v_cndmask_b32_e64 v140, v118, v136, s[6:7]
	s_waitcnt lgkmcnt(5)
	v_cndmask_b32_e64 v141, v119, v137, s[6:7]
	v_lshlrev_b32_e32 v118, 16, v129
	v_and_b32_e32 v119, 0xffff0000, v129
	v_cndmask_b32_e64 v142, v134, v123, s[4:5]
	s_waitcnt lgkmcnt(4)
	v_cndmask_b32_e64 v164, v135, v122, s[4:5]
	v_pk_mul_f32 v[118:119], v[92:93], v[118:119]
	v_lshlrev_b32_e32 v122, 16, v108
	v_and_b32_e32 v123, 0xffff0000, v108
	s_waitcnt lgkmcnt(1)
	v_cndmask_b32_e64 v143, v120, v138, s[6:7]
	s_waitcnt lgkmcnt(0)
	v_cndmask_b32_e64 v165, v121, v139, s[6:7]
	v_lshlrev_b32_e32 v120, 16, v140
	v_and_b32_e32 v121, 0xffff0000, v140
	v_pk_fma_f32 v[118:119], v[84:85], v[122:123], v[118:119]
	ds_bpermute_b32 v131, v193, v109
	v_pk_fma_f32 v[118:119], v[80:81], v[120:121], v[118:119]
	s_waitcnt lgkmcnt(0)
	v_cndmask_b32_e64 v128, v131, v128, s[4:5]
	v_pk_add_f32 v[118:119], v[88:89], v[118:119]
	s_nop 0
	v_mul_f32_e32 v108, 0xbfb8aa3b, v118
	v_exp_f32_e32 v108, v108
	s_nop 0
	v_add_f32_e32 v108, 1.0, v108
	v_rcp_f32_e32 v120, v108
	v_mul_f32_e32 v108, 0xbfb8aa3b, v119
	v_exp_f32_e32 v108, v108
	s_nop 0
	v_add_f32_e32 v108, 1.0, v108
	v_rcp_f32_e32 v121, v108
	v_lshlrev_b32_e32 v108, 16, v109
	v_and_b32_e32 v109, 0xffff0000, v109
	v_pk_mul_f32 v[118:119], v[118:119], v[120:121]
	s_nop 0
	v_pk_mul_f32 v[60:61], v[60:61], v[118:119]
	v_lshlrev_b32_e32 v118, 16, v128
	v_and_b32_e32 v119, 0xffff0000, v128
	v_pk_mul_f32 v[118:119], v[94:95], v[118:119]
	v_lshlrev_b32_e32 v120, 16, v141
	v_and_b32_e32 v121, 0xffff0000, v141
	v_pk_fma_f32 v[108:109], v[86:87], v[108:109], v[118:119]
	s_nop 0
	v_pk_fma_f32 v[108:109], v[82:83], v[120:121], v[108:109]
	v_lshlrev_b32_e32 v120, 16, v110
	v_pk_add_f32 v[108:109], v[90:91], v[108:109]
	v_and_b32_e32 v121, 0xffff0000, v110
	v_mul_f32_e32 v118, 0xbfb8aa3b, v108
	v_mul_f32_e32 v119, 0xbfb8aa3b, v109
	v_exp_f32_e32 v118, v118
	v_exp_f32_e32 v119, v119
	v_add_f32_e32 v118, 1.0, v118
	v_add_f32_e32 v119, 1.0, v119
	v_rcp_f32_e32 v118, v118
	v_rcp_f32_e32 v119, v119
	s_nop 0
	v_pk_mul_f32 v[108:109], v[108:109], v[118:119]
	s_nop 0
	v_pk_mul_f32 v[62:63], v[62:63], v[108:109]
	v_lshlrev_b32_e32 v108, 16, v142
	v_and_b32_e32 v109, 0xffff0000, v142
	v_pk_mul_f32 v[108:109], v[76:77], v[108:109]
	v_lshlrev_b32_e32 v118, 16, v143
	v_and_b32_e32 v119, 0xffff0000, v143
	v_pk_fma_f32 v[108:109], v[68:69], v[120:121], v[108:109]
	s_nop 0
	v_pk_fma_f32 v[108:109], v[64:65], v[118:119], v[108:109]
	s_nop 0
	v_pk_add_f32 v[108:109], v[72:73], v[108:109]
	s_nop 0
	v_mul_f32_e32 v110, 0xbfb8aa3b, v108
	v_exp_f32_e32 v110, v110
	s_nop 0
	v_add_f32_e32 v110, 1.0, v110
	v_rcp_f32_e32 v118, v110
	v_mul_f32_e32 v110, 0xbfb8aa3b, v109
	v_exp_f32_e32 v110, v110
	s_nop 0
	v_add_f32_e32 v110, 1.0, v110
	v_rcp_f32_e32 v119, v110
	v_lshlrev_b32_e32 v110, 16, v111
	v_and_b32_e32 v111, 0xffff0000, v111
	v_pk_mul_f32 v[108:109], v[108:109], v[118:119]
	s_nop 0
	v_pk_mul_f32 v[108:109], v[56:57], v[108:109]
	v_lshlrev_b32_e32 v56, 16, v164
	v_and_b32_e32 v57, 0xffff0000, v164
	v_pk_mul_f32 v[56:57], v[78:79], v[56:57]
	v_lshlrev_b32_e32 v118, 16, v165
	v_and_b32_e32 v119, 0xffff0000, v165
	v_pk_fma_f32 v[56:57], v[70:71], v[110:111], v[56:57]
	s_nop 0
	v_pk_fma_f32 v[56:57], v[66:67], v[118:119], v[56:57]
	ds_bpermute_b32 v118, v225, v102
	v_pk_add_f32 v[56:57], v[74:75], v[56:57]
	ds_bpermute_b32 v119, v225, v103
	v_mul_f32_e32 v110, 0xbfb8aa3b, v56
	v_mul_f32_e32 v111, 0xbfb8aa3b, v57
	v_exp_f32_e32 v110, v110
	v_exp_f32_e32 v111, v111
	s_waitcnt lgkmcnt(1)
	v_cndmask_b32_e64 v123, v138, v118, s[6:7]
	s_waitcnt lgkmcnt(0)
	v_cndmask_b32_e64 v129, v139, v119, s[6:7]
	v_add_f32_e32 v110, 1.0, v110
	v_add_f32_e32 v111, 1.0, v111
	v_rcp_f32_e32 v110, v110
	v_rcp_f32_e32 v111, v111
	s_nop 0
	v_pk_mul_f32 v[56:57], v[56:57], v[110:111]
	s_nop 0
	v_pk_mul_f32 v[110:111], v[58:59], v[56:57]
	v_cvt_pk_bf16_f32 v57, v62, v63
	ds_bpermute_b32 v62, v193, v104
	v_cvt_pk_bf16_f32 v59, v110, v111
	ds_bpermute_b32 v110, v225, v100
	v_cvt_pk_bf16_f32 v56, v60, v61
	v_cvt_pk_bf16_f32 v58, v108, v109
	global_store_dwordx4 v[156:157], v[56:59], off offset:256
	v_lshlrev_b32_e32 v60, 16, v104
	v_and_b32_e32 v61, 0xffff0000, v104
	s_waitcnt lgkmcnt(1)
	v_cndmask_b32_e64 v57, v62, v130, s[4:5]
	v_lshlrev_b32_e32 v56, 16, v57
	v_and_b32_e32 v57, 0xffff0000, v57
	s_waitcnt lgkmcnt(0)
	v_cndmask_b32_e64 v59, v136, v110, s[6:7]
	v_pk_mul_f32 v[56:57], v[92:93], v[56:57]
	v_lshlrev_b32_e32 v58, 16, v59
	v_and_b32_e32 v59, 0xffff0000, v59
	v_pk_fma_f32 v[56:57], v[84:85], v[60:61], v[56:57]
	ds_bpermute_b32 v63, v193, v105
	v_pk_fma_f32 v[56:57], v[80:81], v[58:59], v[56:57]
	ds_bpermute_b32 v111, v225, v101
	v_pk_add_f32 v[56:57], v[88:89], v[56:57]
	v_lshlrev_b32_e32 v60, 16, v105
	v_mul_f32_e32 v58, 0xbfb8aa3b, v56
	v_mul_f32_e32 v59, 0xbfb8aa3b, v57
	v_exp_f32_e32 v58, v58
	v_exp_f32_e32 v59, v59
	s_waitcnt lgkmcnt(1)
	v_cndmask_b32_e64 v120, v63, v131, s[4:5]
	s_waitcnt lgkmcnt(0)
	v_cndmask_b32_e64 v121, v137, v111, s[6:7]
	v_add_f32_e32 v58, 1.0, v58
	v_add_f32_e32 v59, 1.0, v59
	v_rcp_f32_e32 v58, v58
	v_rcp_f32_e32 v59, v59
	v_and_b32_e32 v61, 0xffff0000, v105
	ds_bpermute_b32 v108, v193, v106
	ds_bpermute_b32 v109, v193, v107
	v_pk_mul_f32 v[56:57], v[56:57], v[58:59]
	v_lshlrev_b32_e32 v58, 16, v121
	v_pk_mul_f32 v[52:53], v[52:53], v[56:57]
	v_lshlrev_b32_e32 v56, 16, v120
	v_and_b32_e32 v57, 0xffff0000, v120
	v_pk_mul_f32 v[56:57], v[94:95], v[56:57]
	v_and_b32_e32 v59, 0xffff0000, v121
	v_pk_fma_f32 v[56:57], v[86:87], v[60:61], v[56:57]
	s_waitcnt lgkmcnt(1)
	v_cndmask_b32_e64 v122, v108, v134, s[4:5]
	v_pk_fma_f32 v[56:57], v[82:83], v[58:59], v[56:57]
	v_lshlrev_b32_e32 v60, 16, v106
	v_pk_add_f32 v[56:57], v[90:91], v[56:57]
	v_and_b32_e32 v61, 0xffff0000, v106
	v_mul_f32_e32 v58, 0xbfb8aa3b, v56
	v_mul_f32_e32 v59, 0xbfb8aa3b, v57
	v_exp_f32_e32 v58, v58
	v_exp_f32_e32 v59, v59
	s_waitcnt lgkmcnt(0)
	v_cndmask_b32_e64 v128, v109, v135, s[4:5]
	v_add_f32_e32 v58, 1.0, v58
	v_add_f32_e32 v59, 1.0, v59
	v_rcp_f32_e32 v58, v58
	v_rcp_f32_e32 v59, v59
	s_nop 0
	v_pk_mul_f32 v[56:57], v[56:57], v[58:59]
	s_nop 0
	v_pk_mul_f32 v[54:55], v[54:55], v[56:57]
	v_lshlrev_b32_e32 v56, 16, v122
	v_and_b32_e32 v57, 0xffff0000, v122
	v_pk_mul_f32 v[56:57], v[76:77], v[56:57]
	v_lshlrev_b32_e32 v58, 16, v123
	v_and_b32_e32 v59, 0xffff0000, v123
	v_pk_fma_f32 v[56:57], v[68:69], v[60:61], v[56:57]
	v_lshlrev_b32_e32 v60, 16, v107
	v_pk_fma_f32 v[56:57], v[64:65], v[58:59], v[56:57]
	v_and_b32_e32 v61, 0xffff0000, v107
	v_pk_add_f32 v[56:57], v[72:73], v[56:57]
	s_nop 0
	v_mul_f32_e32 v58, 0xbfb8aa3b, v56
	v_mul_f32_e32 v59, 0xbfb8aa3b, v57
	v_exp_f32_e32 v58, v58
	v_exp_f32_e32 v59, v59
	v_add_f32_e32 v58, 1.0, v58
	v_add_f32_e32 v59, 1.0, v59
	v_rcp_f32_e32 v58, v58
	v_rcp_f32_e32 v59, v59
	s_nop 0
	v_pk_mul_f32 v[56:57], v[56:57], v[58:59]
	s_nop 0
	v_pk_mul_f32 v[56:57], v[48:49], v[56:57]
	v_lshlrev_b32_e32 v48, 16, v128
	v_and_b32_e32 v49, 0xffff0000, v128
	v_pk_mul_f32 v[48:49], v[78:79], v[48:49]
	v_lshlrev_b32_e32 v58, 16, v129
	v_and_b32_e32 v59, 0xffff0000, v129
	v_pk_fma_f32 v[48:49], v[70:71], v[60:61], v[48:49]
	ds_bpermute_b32 v60, v225, v98
	v_pk_fma_f32 v[48:49], v[66:67], v[58:59], v[48:49]
	ds_bpermute_b32 v61, v225, v99
	v_pk_add_f32 v[48:49], v[74:75], v[48:49]
	s_waitcnt lgkmcnt(1)
	v_cndmask_b32_e64 v105, v118, v60, s[6:7]
	v_mul_f32_e32 v58, 0xbfb8aa3b, v48
	v_mul_f32_e32 v59, 0xbfb8aa3b, v49
	v_exp_f32_e32 v58, v58
	v_exp_f32_e32 v59, v59
	s_waitcnt lgkmcnt(0)
	v_cndmask_b32_e64 v107, v119, v61, s[6:7]
	v_add_f32_e32 v58, 1.0, v58
	v_add_f32_e32 v59, 1.0, v59
	v_rcp_f32_e32 v58, v58
	v_rcp_f32_e32 v59, v59
	s_nop 0
	v_pk_mul_f32 v[48:49], v[48:49], v[58:59]
	s_nop 0
	v_pk_mul_f32 v[58:59], v[50:51], v[48:49]
	v_cvt_pk_bf16_f32 v49, v54, v55
	ds_bpermute_b32 v54, v193, v100
	v_cvt_pk_bf16_f32 v51, v58, v59
	ds_bpermute_b32 v58, v225, v96
	v_cvt_pk_bf16_f32 v48, v52, v53
	v_cvt_pk_bf16_f32 v50, v56, v57
	global_store_dwordx4 v[146:147], v[48:51], off offset:256
	v_lshlrev_b32_e32 v52, 16, v100
	v_and_b32_e32 v53, 0xffff0000, v100
	s_waitcnt lgkmcnt(1)
	v_cndmask_b32_e64 v49, v54, v62, s[4:5]
	v_lshlrev_b32_e32 v48, 16, v49
	v_and_b32_e32 v49, 0xffff0000, v49
	s_waitcnt lgkmcnt(0)
	v_cndmask_b32_e64 v51, v110, v58, s[6:7]
	v_pk_mul_f32 v[48:49], v[92:93], v[48:49]
	v_lshlrev_b32_e32 v50, 16, v51
	v_and_b32_e32 v51, 0xffff0000, v51
	v_pk_fma_f32 v[48:49], v[84:85], v[52:53], v[48:49]
	ds_bpermute_b32 v55, v193, v101
	v_pk_fma_f32 v[48:49], v[80:81], v[50:51], v[48:49]
	ds_bpermute_b32 v59, v225, v97
	v_pk_add_f32 v[48:49], v[88:89], v[48:49]
	v_lshlrev_b32_e32 v52, 16, v101
	v_mul_f32_e32 v50, 0xbfb8aa3b, v48
	v_mul_f32_e32 v51, 0xbfb8aa3b, v49
	v_exp_f32_e32 v50, v50
	v_exp_f32_e32 v51, v51
	s_waitcnt lgkmcnt(1)
	v_cndmask_b32_e64 v62, v55, v63, s[4:5]
	s_waitcnt lgkmcnt(0)
	v_cndmask_b32_e64 v63, v111, v59, s[6:7]
	v_add_f32_e32 v50, 1.0, v50
	v_add_f32_e32 v51, 1.0, v51
	v_rcp_f32_e32 v50, v50
	v_rcp_f32_e32 v51, v51
	v_and_b32_e32 v53, 0xffff0000, v101
	ds_bpermute_b32 v56, v193, v102
	ds_bpermute_b32 v57, v193, v103
	v_pk_mul_f32 v[48:49], v[48:49], v[50:51]
	v_lshlrev_b32_e32 v50, 16, v63
	v_pk_mul_f32 v[44:45], v[44:45], v[48:49]
	v_lshlrev_b32_e32 v48, 16, v62
	v_and_b32_e32 v49, 0xffff0000, v62
	v_pk_mul_f32 v[48:49], v[94:95], v[48:49]
	v_and_b32_e32 v51, 0xffff0000, v63
	v_pk_fma_f32 v[48:49], v[86:87], v[52:53], v[48:49]
	s_waitcnt lgkmcnt(1)
	v_cndmask_b32_e64 v104, v56, v108, s[4:5]
	v_pk_fma_f32 v[48:49], v[82:83], v[50:51], v[48:49]
	v_lshlrev_b32_e32 v52, 16, v102
	v_pk_add_f32 v[48:49], v[90:91], v[48:49]
	v_and_b32_e32 v53, 0xffff0000, v102
	v_mul_f32_e32 v50, 0xbfb8aa3b, v48
	v_mul_f32_e32 v51, 0xbfb8aa3b, v49
	v_exp_f32_e32 v50, v50
	v_exp_f32_e32 v51, v51
	s_waitcnt lgkmcnt(0)
	v_cndmask_b32_e64 v106, v57, v109, s[4:5]
	v_add_f32_e32 v50, 1.0, v50
	v_add_f32_e32 v51, 1.0, v51
	v_rcp_f32_e32 v50, v50
	v_rcp_f32_e32 v51, v51
	s_nop 0
	v_pk_mul_f32 v[48:49], v[48:49], v[50:51]
	s_nop 0
	v_pk_mul_f32 v[46:47], v[46:47], v[48:49]
	v_lshlrev_b32_e32 v48, 16, v104
	v_and_b32_e32 v49, 0xffff0000, v104
	v_pk_mul_f32 v[48:49], v[76:77], v[48:49]
	v_lshlrev_b32_e32 v50, 16, v105
	v_and_b32_e32 v51, 0xffff0000, v105
	v_pk_fma_f32 v[48:49], v[68:69], v[52:53], v[48:49]
	v_lshlrev_b32_e32 v52, 16, v103
	v_pk_fma_f32 v[48:49], v[64:65], v[50:51], v[48:49]
	v_and_b32_e32 v53, 0xffff0000, v103
	v_pk_add_f32 v[48:49], v[72:73], v[48:49]
	s_nop 0
	v_mul_f32_e32 v50, 0xbfb8aa3b, v48
	v_mul_f32_e32 v51, 0xbfb8aa3b, v49
	v_exp_f32_e32 v50, v50
	v_exp_f32_e32 v51, v51
	v_add_f32_e32 v50, 1.0, v50
	v_add_f32_e32 v51, 1.0, v51
	v_rcp_f32_e32 v50, v50
	v_rcp_f32_e32 v51, v51
	s_nop 0
	v_pk_mul_f32 v[48:49], v[48:49], v[50:51]
	s_nop 0
	v_pk_mul_f32 v[48:49], v[40:41], v[48:49]
	v_lshlrev_b32_e32 v40, 16, v106
	v_and_b32_e32 v41, 0xffff0000, v106
	v_pk_mul_f32 v[40:41], v[78:79], v[40:41]
	v_lshlrev_b32_e32 v50, 16, v107
	v_and_b32_e32 v51, 0xffff0000, v107
	v_pk_fma_f32 v[40:41], v[70:71], v[52:53], v[40:41]
	s_nop 0
	v_pk_fma_f32 v[40:41], v[66:67], v[50:51], v[40:41]
	s_nop 0
	v_pk_add_f32 v[40:41], v[74:75], v[40:41]
	s_nop 0
	v_mul_f32_e32 v50, 0xbfb8aa3b, v40
	v_mul_f32_e32 v51, 0xbfb8aa3b, v41
	v_exp_f32_e32 v50, v50
	v_exp_f32_e32 v51, v51
	v_add_f32_e32 v50, 1.0, v50
	v_add_f32_e32 v51, 1.0, v51
	v_rcp_f32_e32 v50, v50
	v_rcp_f32_e32 v51, v51
	s_nop 0
	v_pk_mul_f32 v[40:41], v[40:41], v[50:51]
	s_nop 0
	v_pk_mul_f32 v[50:51], v[42:43], v[40:41]
	v_cvt_pk_bf16_f32 v40, v44, v45
	v_cvt_pk_bf16_f32 v41, v46, v47
	v_cvt_pk_bf16_f32 v42, v48, v49
	v_cvt_pk_bf16_f32 v43, v50, v51
	global_store_dwordx4 v[148:149], v[40:43], off offset:256
	ds_bpermute_b32 v40, v193, v96
	ds_bpermute_b32 v41, v193, v97
	ds_bpermute_b32 v42, v193, v98
	ds_bpermute_b32 v43, v193, v99
	v_cndmask_b32_e64 v45, v58, v117, s[6:7]
	s_waitcnt lgkmcnt(3)
	v_cndmask_b32_e64 v44, v40, v54, s[4:5]
	s_waitcnt lgkmcnt(2)
	v_cndmask_b32_e64 v46, v41, v55, s[4:5]
	v_lshlrev_b32_e32 v40, 16, v44
	v_and_b32_e32 v41, 0xffff0000, v44
	s_waitcnt lgkmcnt(1)
	v_cndmask_b32_e64 v48, v42, v56, s[4:5]
	s_waitcnt lgkmcnt(0)
	v_cndmask_b32_e64 v50, v43, v57, s[4:5]
	v_lshlrev_b32_e32 v42, 16, v45
	v_and_b32_e32 v43, 0xffff0000, v45
	v_pk_mul_f32 v[40:41], v[92:93], v[40:41]
	v_lshlrev_b32_e32 v44, 16, v96
	v_and_b32_e32 v45, 0xffff0000, v96
	v_pk_fma_f32 v[40:41], v[84:85], v[44:45], v[40:41]
	v_cndmask_b32_e64 v47, v59, v116, s[6:7]
	v_pk_fma_f32 v[40:41], v[80:81], v[42:43], v[40:41]
	v_lshlrev_b32_e32 v44, 16, v97
	v_pk_add_f32 v[40:41], v[88:89], v[40:41]
	v_and_b32_e32 v45, 0xffff0000, v97
	v_mul_f32_e32 v42, 0xbfb8aa3b, v40
	v_mul_f32_e32 v43, 0xbfb8aa3b, v41
	v_exp_f32_e32 v42, v42
	v_exp_f32_e32 v43, v43
	v_cndmask_b32_e64 v49, v60, v115, s[6:7]
	v_cndmask_b32_e64 v51, v61, v114, s[6:7]
	v_add_f32_e32 v42, 1.0, v42
	v_add_f32_e32 v43, 1.0, v43
	v_rcp_f32_e32 v42, v42
	v_rcp_f32_e32 v43, v43
	s_nop 0
	v_pk_mul_f32 v[40:41], v[40:41], v[42:43]
	s_nop 0
	v_pk_mul_f32 v[36:37], v[36:37], v[40:41]
	v_lshlrev_b32_e32 v40, 16, v46
	v_and_b32_e32 v41, 0xffff0000, v46
	v_pk_mul_f32 v[40:41], v[94:95], v[40:41]
	v_lshlrev_b32_e32 v42, 16, v47
	v_and_b32_e32 v43, 0xffff0000, v47
	v_pk_fma_f32 v[40:41], v[86:87], v[44:45], v[40:41]
	v_lshlrev_b32_e32 v44, 16, v98
	v_pk_fma_f32 v[40:41], v[82:83], v[42:43], v[40:41]
	v_and_b32_e32 v45, 0xffff0000, v98
	v_pk_add_f32 v[40:41], v[90:91], v[40:41]
	s_nop 0
	v_mul_f32_e32 v42, 0xbfb8aa3b, v40
	v_mul_f32_e32 v43, 0xbfb8aa3b, v41
	v_exp_f32_e32 v42, v42
	v_exp_f32_e32 v43, v43
	v_add_f32_e32 v42, 1.0, v42
	v_add_f32_e32 v43, 1.0, v43
	v_rcp_f32_e32 v42, v42
	v_rcp_f32_e32 v43, v43
	s_nop 0
	v_pk_mul_f32 v[40:41], v[40:41], v[42:43]
	s_nop 0
	v_pk_mul_f32 v[38:39], v[38:39], v[40:41]
	v_lshlrev_b32_e32 v40, 16, v48
	v_and_b32_e32 v41, 0xffff0000, v48
	v_pk_mul_f32 v[40:41], v[76:77], v[40:41]
	v_lshlrev_b32_e32 v42, 16, v49
	v_and_b32_e32 v43, 0xffff0000, v49
	v_pk_fma_f32 v[40:41], v[68:69], v[44:45], v[40:41]
	v_lshlrev_b32_e32 v44, 16, v99
	v_pk_fma_f32 v[40:41], v[64:65], v[42:43], v[40:41]
	v_and_b32_e32 v45, 0xffff0000, v99
	v_pk_add_f32 v[40:41], v[72:73], v[40:41]
	s_nop 0
	v_mul_f32_e32 v42, 0xbfb8aa3b, v40
	v_mul_f32_e32 v43, 0xbfb8aa3b, v41
	v_exp_f32_e32 v42, v42
	v_exp_f32_e32 v43, v43
	v_add_f32_e32 v42, 1.0, v42
	v_add_f32_e32 v43, 1.0, v43
	v_rcp_f32_e32 v42, v42
	v_rcp_f32_e32 v43, v43
	s_nop 0
	v_pk_mul_f32 v[40:41], v[40:41], v[42:43]
	s_nop 0
	v_pk_mul_f32 v[40:41], v[32:33], v[40:41]
	v_lshlrev_b32_e32 v32, 16, v50
	v_and_b32_e32 v33, 0xffff0000, v50
	v_pk_mul_f32 v[32:33], v[78:79], v[32:33]
	v_lshlrev_b32_e32 v42, 16, v51
	v_and_b32_e32 v43, 0xffff0000, v51
	v_pk_fma_f32 v[32:33], v[70:71], v[44:45], v[32:33]
	s_nop 0
	v_pk_fma_f32 v[32:33], v[66:67], v[42:43], v[32:33]
	s_nop 0
	v_pk_add_f32 v[32:33], v[74:75], v[32:33]
	s_nop 0
	v_mul_f32_e32 v42, 0xbfb8aa3b, v32
	v_mul_f32_e32 v43, 0xbfb8aa3b, v33
	v_exp_f32_e32 v42, v42
	v_exp_f32_e32 v43, v43
	v_add_f32_e32 v42, 1.0, v42
	v_add_f32_e32 v43, 1.0, v43
	v_rcp_f32_e32 v42, v42
	v_rcp_f32_e32 v43, v43
	s_nop 0
	v_pk_mul_f32 v[32:33], v[32:33], v[42:43]
	s_nop 0
	v_pk_mul_f32 v[42:43], v[34:35], v[32:33]
	v_cvt_pk_bf16_f32 v32, v36, v37
	v_cvt_pk_bf16_f32 v33, v38, v39
	v_cvt_pk_bf16_f32 v34, v40, v41
	v_cvt_pk_bf16_f32 v35, v42, v43
	global_store_dwordx4 v[144:145], v[32:35], off offset:256
	global_load_dwordx4 v[48:51], v[150:151], off offset:256
	global_load_dwordx4 v[44:47], v[152:153], off offset:256
	global_load_dwordx4 v[40:43], v[154:155], off offset:256
	global_load_dwordx4 v[32:35], v[158:159], off offset:256
	global_load_dwordx4 v[52:55], v[162:163], off offset:256
	global_load_dwordx4 v[36:39], v[160:161], off offset:256
	s_waitcnt vmcnt(5)
	ds_bpermute_b32 v58, v193, v48
	ds_bpermute_b32 v56, v225, v48
	ds_bpermute_b32 v59, v193, v49
	s_waitcnt vmcnt(4)
	ds_bpermute_b32 v96, v225, v44
	ds_bpermute_b32 v57, v225, v49
	ds_bpermute_b32 v60, v193, v50
	ds_bpermute_b32 v62, v193, v51
	ds_bpermute_b32 v97, v225, v45
	s_waitcnt vmcnt(1)
	v_cndmask_b32_e64 v52, v52, 0, s[22:23]
	v_cndmask_b32_e64 v53, v53, 0, s[22:23]
	s_waitcnt lgkmcnt(7)
	v_cndmask_b32_e64 v100, v58, v52, s[4:5]
	v_cndmask_b32_e64 v55, v55, 0, s[22:23]
	v_cndmask_b32_e64 v54, v54, 0, s[22:23]
	s_waitcnt lgkmcnt(4)
	v_cndmask_b32_e64 v56, v56, v96, s[6:7]
	v_cndmask_b32_e64 v101, v59, v53, s[4:5]
	v_lshlrev_b32_e32 v52, 16, v100
	v_and_b32_e32 v53, 0xffff0000, v100
	s_waitcnt lgkmcnt(0)
	v_cndmask_b32_e64 v102, v57, v97, s[6:7]
	v_cndmask_b32_e64 v103, v60, v54, s[4:5]
	v_cndmask_b32_e64 v104, v62, v55, s[4:5]
	v_lshlrev_b32_e32 v54, 16, v56
	v_and_b32_e32 v55, 0xffff0000, v56
	v_pk_mul_f32 v[52:53], v[92:93], v[52:53]
	v_lshlrev_b32_e32 v56, 16, v48
	v_and_b32_e32 v57, 0xffff0000, v48
	v_pk_fma_f32 v[52:53], v[84:85], v[56:57], v[52:53]
	ds_bpermute_b32 v61, v225, v50
	v_pk_fma_f32 v[52:53], v[80:81], v[54:55], v[52:53]
	ds_bpermute_b32 v98, v225, v46
	v_pk_add_f32 v[52:53], v[88:89], v[52:53]
	ds_bpermute_b32 v63, v225, v51
	v_mul_f32_e32 v48, 0xbfb8aa3b, v52
	v_exp_f32_e32 v48, v48
	s_waitcnt lgkmcnt(1)
	v_cndmask_b32_e64 v61, v61, v98, s[6:7]
	ds_bpermute_b32 v99, v225, v47
	v_add_f32_e32 v48, 1.0, v48
	v_rcp_f32_e32 v54, v48
	v_mul_f32_e32 v48, 0xbfb8aa3b, v53
	v_exp_f32_e32 v48, v48
	s_waitcnt lgkmcnt(0)
	v_cndmask_b32_e64 v63, v63, v99, s[6:7]
	v_add_f32_e32 v48, 1.0, v48
	v_rcp_f32_e32 v55, v48
	v_lshlrev_b32_e32 v48, 16, v49
	v_and_b32_e32 v49, 0xffff0000, v49
	v_pk_mul_f32 v[52:53], v[52:53], v[54:55]
	s_nop 0
	v_pk_mul_f32 v[28:29], v[28:29], v[52:53]
	v_lshlrev_b32_e32 v52, 16, v101
	v_and_b32_e32 v53, 0xffff0000, v101
	v_pk_mul_f32 v[52:53], v[94:95], v[52:53]
	v_lshlrev_b32_e32 v54, 16, v102
	v_and_b32_e32 v55, 0xffff0000, v102
	v_pk_fma_f32 v[48:49], v[86:87], v[48:49], v[52:53]
	s_nop 0
	v_pk_fma_f32 v[48:49], v[82:83], v[54:55], v[48:49]
	v_lshlrev_b32_e32 v54, 16, v50
	v_pk_add_f32 v[48:49], v[90:91], v[48:49]
	v_and_b32_e32 v55, 0xffff0000, v50
	v_mul_f32_e32 v52, 0xbfb8aa3b, v48
	v_mul_f32_e32 v53, 0xbfb8aa3b, v49
	v_exp_f32_e32 v52, v52
	v_exp_f32_e32 v53, v53
	v_add_f32_e32 v52, 1.0, v52
	v_add_f32_e32 v53, 1.0, v53
	v_rcp_f32_e32 v52, v52
	v_rcp_f32_e32 v53, v53
	s_nop 0
	v_pk_mul_f32 v[48:49], v[48:49], v[52:53]
	s_nop 0
	v_pk_mul_f32 v[30:31], v[30:31], v[48:49]
	v_lshlrev_b32_e32 v48, 16, v103
	v_and_b32_e32 v49, 0xffff0000, v103
	v_pk_mul_f32 v[48:49], v[76:77], v[48:49]
	v_lshlrev_b32_e32 v52, 16, v61
	v_and_b32_e32 v53, 0xffff0000, v61
	v_pk_fma_f32 v[48:49], v[68:69], v[54:55], v[48:49]
	s_nop 0
	v_pk_fma_f32 v[48:49], v[64:65], v[52:53], v[48:49]
	s_nop 0
	v_pk_add_f32 v[48:49], v[72:73], v[48:49]
	s_nop 0
	v_mul_f32_e32 v50, 0xbfb8aa3b, v48
	v_exp_f32_e32 v50, v50
	s_nop 0
	v_add_f32_e32 v50, 1.0, v50
	v_rcp_f32_e32 v52, v50
	v_mul_f32_e32 v50, 0xbfb8aa3b, v49
	v_exp_f32_e32 v50, v50
	s_nop 0
	v_add_f32_e32 v50, 1.0, v50
	v_rcp_f32_e32 v53, v50
	v_lshlrev_b32_e32 v50, 16, v51
	v_and_b32_e32 v51, 0xffff0000, v51
	v_pk_mul_f32 v[48:49], v[48:49], v[52:53]
	s_nop 0
	v_pk_mul_f32 v[48:49], v[24:25], v[48:49]
	v_lshlrev_b32_e32 v24, 16, v104
	v_and_b32_e32 v25, 0xffff0000, v104
	v_pk_mul_f32 v[24:25], v[78:79], v[24:25]
	v_lshlrev_b32_e32 v52, 16, v63
	v_and_b32_e32 v53, 0xffff0000, v63
	v_pk_fma_f32 v[24:25], v[70:71], v[50:51], v[24:25]
	s_nop 0
	v_pk_fma_f32 v[24:25], v[66:67], v[52:53], v[24:25]
	ds_bpermute_b32 v52, v225, v42
	v_pk_add_f32 v[24:25], v[74:75], v[24:25]
	ds_bpermute_b32 v53, v225, v43
	v_mul_f32_e32 v50, 0xbfb8aa3b, v24
	v_mul_f32_e32 v51, 0xbfb8aa3b, v25
	v_exp_f32_e32 v50, v50
	v_exp_f32_e32 v51, v51
	s_waitcnt lgkmcnt(1)
	v_cndmask_b32_e64 v57, v98, v52, s[6:7]
	v_add_f32_e32 v50, 1.0, v50
	v_add_f32_e32 v51, 1.0, v51
	v_rcp_f32_e32 v50, v50
	v_rcp_f32_e32 v51, v51
	s_nop 0
	v_pk_mul_f32 v[24:25], v[24:25], v[50:51]
	s_nop 0
	v_pk_mul_f32 v[50:51], v[26:27], v[24:25]
	v_cvt_pk_bf16_f32 v25, v30, v31
	ds_bpermute_b32 v30, v193, v44
	v_cvt_pk_bf16_f32 v27, v50, v51
	ds_bpermute_b32 v50, v225, v40
	v_cvt_pk_bf16_f32 v24, v28, v29
	v_cvt_pk_bf16_f32 v26, v48, v49
	global_store_dwordx4 v[124:125], v[24:27], off offset:256
	v_lshlrev_b32_e32 v28, 16, v44
	v_and_b32_e32 v29, 0xffff0000, v44
	s_waitcnt lgkmcnt(1)
	v_cndmask_b32_e64 v25, v30, v58, s[4:5]
	v_lshlrev_b32_e32 v24, 16, v25
	v_and_b32_e32 v25, 0xffff0000, v25
	s_waitcnt lgkmcnt(0)
	v_cndmask_b32_e64 v27, v96, v50, s[6:7]
	v_pk_mul_f32 v[24:25], v[92:93], v[24:25]
	v_lshlrev_b32_e32 v26, 16, v27
	v_and_b32_e32 v27, 0xffff0000, v27
	v_pk_fma_f32 v[24:25], v[84:85], v[28:29], v[24:25]
	ds_bpermute_b32 v31, v193, v45
	v_pk_fma_f32 v[24:25], v[80:81], v[26:27], v[24:25]
	ds_bpermute_b32 v51, v225, v41
	v_pk_add_f32 v[24:25], v[88:89], v[24:25]
	v_lshlrev_b32_e32 v28, 16, v45
	v_mul_f32_e32 v26, 0xbfb8aa3b, v24
	v_mul_f32_e32 v27, 0xbfb8aa3b, v25
	v_exp_f32_e32 v26, v26
	v_exp_f32_e32 v27, v27
	s_waitcnt lgkmcnt(1)
	v_cndmask_b32_e64 v54, v31, v59, s[4:5]
	s_waitcnt lgkmcnt(0)
	v_cndmask_b32_e64 v55, v97, v51, s[6:7]
	v_add_f32_e32 v26, 1.0, v26
	v_add_f32_e32 v27, 1.0, v27
	v_rcp_f32_e32 v26, v26
	v_rcp_f32_e32 v27, v27
	v_and_b32_e32 v29, 0xffff0000, v45
	ds_bpermute_b32 v48, v193, v46
	ds_bpermute_b32 v49, v193, v47
	v_pk_mul_f32 v[24:25], v[24:25], v[26:27]
	v_lshlrev_b32_e32 v26, 16, v55
	v_pk_mul_f32 v[20:21], v[20:21], v[24:25]
	v_lshlrev_b32_e32 v24, 16, v54
	v_and_b32_e32 v25, 0xffff0000, v54
	v_pk_mul_f32 v[24:25], v[94:95], v[24:25]
	v_and_b32_e32 v27, 0xffff0000, v55
	v_pk_fma_f32 v[24:25], v[86:87], v[28:29], v[24:25]
	s_waitcnt lgkmcnt(1)
	v_cndmask_b32_e64 v56, v48, v60, s[4:5]
	v_pk_fma_f32 v[24:25], v[82:83], v[26:27], v[24:25]
	v_lshlrev_b32_e32 v28, 16, v46
	v_pk_add_f32 v[24:25], v[90:91], v[24:25]
	v_and_b32_e32 v29, 0xffff0000, v46
	v_mul_f32_e32 v26, 0xbfb8aa3b, v24
	v_mul_f32_e32 v27, 0xbfb8aa3b, v25
	v_exp_f32_e32 v26, v26
	v_exp_f32_e32 v27, v27
	s_waitcnt lgkmcnt(0)
	v_cndmask_b32_e64 v58, v49, v62, s[4:5]
	v_cndmask_b32_e64 v59, v99, v53, s[6:7]
	v_add_f32_e32 v26, 1.0, v26
	v_add_f32_e32 v27, 1.0, v27
	v_rcp_f32_e32 v26, v26
	v_rcp_f32_e32 v27, v27
	s_nop 0
	v_pk_mul_f32 v[24:25], v[24:25], v[26:27]
	s_nop 0
	v_pk_mul_f32 v[22:23], v[22:23], v[24:25]
	v_lshlrev_b32_e32 v24, 16, v56
	v_and_b32_e32 v25, 0xffff0000, v56
	v_pk_mul_f32 v[24:25], v[76:77], v[24:25]
	v_lshlrev_b32_e32 v26, 16, v57
	v_and_b32_e32 v27, 0xffff0000, v57
	v_pk_fma_f32 v[24:25], v[68:69], v[28:29], v[24:25]
	v_lshlrev_b32_e32 v28, 16, v47
	v_pk_fma_f32 v[24:25], v[64:65], v[26:27], v[24:25]
	v_and_b32_e32 v29, 0xffff0000, v47
	v_pk_add_f32 v[24:25], v[72:73], v[24:25]
	s_nop 0
	v_mul_f32_e32 v26, 0xbfb8aa3b, v24
	v_mul_f32_e32 v27, 0xbfb8aa3b, v25
	v_exp_f32_e32 v26, v26
	v_exp_f32_e32 v27, v27
	v_add_f32_e32 v26, 1.0, v26
	v_add_f32_e32 v27, 1.0, v27
	v_rcp_f32_e32 v26, v26
	v_rcp_f32_e32 v27, v27
	s_nop 0
	v_pk_mul_f32 v[24:25], v[24:25], v[26:27]
	s_nop 0
	v_pk_mul_f32 v[24:25], v[16:17], v[24:25]
	v_lshlrev_b32_e32 v16, 16, v58
	v_and_b32_e32 v17, 0xffff0000, v58
	v_pk_mul_f32 v[16:17], v[78:79], v[16:17]
	v_lshlrev_b32_e32 v26, 16, v59
	v_and_b32_e32 v27, 0xffff0000, v59
	v_pk_fma_f32 v[16:17], v[70:71], v[28:29], v[16:17]
	ds_bpermute_b32 v28, v225, v34
	v_pk_fma_f32 v[16:17], v[66:67], v[26:27], v[16:17]
	ds_bpermute_b32 v29, v225, v35
	v_pk_add_f32 v[16:17], v[74:75], v[16:17]
	s_waitcnt lgkmcnt(1)
	v_cndmask_b32_e64 v45, v52, v28, s[6:7]
	v_mul_f32_e32 v26, 0xbfb8aa3b, v16
	v_mul_f32_e32 v27, 0xbfb8aa3b, v17
	v_exp_f32_e32 v26, v26
	v_exp_f32_e32 v27, v27
	s_waitcnt lgkmcnt(0)
	v_cndmask_b32_e64 v47, v53, v29, s[6:7]
	v_add_f32_e32 v26, 1.0, v26
	v_add_f32_e32 v27, 1.0, v27
	v_rcp_f32_e32 v26, v26
	v_rcp_f32_e32 v27, v27
	s_nop 0
	v_pk_mul_f32 v[16:17], v[16:17], v[26:27]
	s_nop 0
	v_pk_mul_f32 v[26:27], v[18:19], v[16:17]
	v_cvt_pk_bf16_f32 v17, v22, v23
	ds_bpermute_b32 v22, v193, v40
	v_cvt_pk_bf16_f32 v19, v26, v27
	ds_bpermute_b32 v26, v225, v32
	v_cvt_pk_bf16_f32 v16, v20, v21
	v_cvt_pk_bf16_f32 v18, v24, v25
	global_store_dwordx4 v[126:127], v[16:19], off offset:256
	v_lshlrev_b32_e32 v20, 16, v40
	v_and_b32_e32 v21, 0xffff0000, v40
	s_waitcnt lgkmcnt(1)
	v_cndmask_b32_e64 v17, v22, v30, s[4:5]
	v_lshlrev_b32_e32 v16, 16, v17
	v_and_b32_e32 v17, 0xffff0000, v17
	s_waitcnt lgkmcnt(0)
	v_cndmask_b32_e64 v19, v50, v26, s[6:7]
	v_pk_mul_f32 v[16:17], v[92:93], v[16:17]
	v_lshlrev_b32_e32 v18, 16, v19
	v_and_b32_e32 v19, 0xffff0000, v19
	v_pk_fma_f32 v[16:17], v[84:85], v[20:21], v[16:17]
	ds_bpermute_b32 v23, v193, v41
	v_pk_fma_f32 v[16:17], v[80:81], v[18:19], v[16:17]
	ds_bpermute_b32 v27, v225, v33
	v_pk_add_f32 v[16:17], v[88:89], v[16:17]
	v_lshlrev_b32_e32 v20, 16, v41
	v_mul_f32_e32 v18, 0xbfb8aa3b, v16
	v_mul_f32_e32 v19, 0xbfb8aa3b, v17
	v_exp_f32_e32 v18, v18
	v_exp_f32_e32 v19, v19
	s_waitcnt lgkmcnt(1)
	v_cndmask_b32_e64 v30, v23, v31, s[4:5]
	s_waitcnt lgkmcnt(0)
	v_cndmask_b32_e64 v31, v51, v27, s[6:7]
	v_add_f32_e32 v18, 1.0, v18
	v_add_f32_e32 v19, 1.0, v19
	v_rcp_f32_e32 v18, v18
	v_rcp_f32_e32 v19, v19
	v_and_b32_e32 v21, 0xffff0000, v41
	ds_bpermute_b32 v24, v193, v42
	ds_bpermute_b32 v25, v193, v43
	v_pk_mul_f32 v[16:17], v[16:17], v[18:19]
	v_lshlrev_b32_e32 v18, 16, v31
	v_pk_mul_f32 v[12:13], v[12:13], v[16:17]
	v_lshlrev_b32_e32 v16, 16, v30
	v_and_b32_e32 v17, 0xffff0000, v30
	v_pk_mul_f32 v[16:17], v[94:95], v[16:17]
	v_and_b32_e32 v19, 0xffff0000, v31
	v_pk_fma_f32 v[16:17], v[86:87], v[20:21], v[16:17]
	s_waitcnt lgkmcnt(1)
	v_cndmask_b32_e64 v44, v24, v48, s[4:5]
	v_pk_fma_f32 v[16:17], v[82:83], v[18:19], v[16:17]
	v_lshlrev_b32_e32 v20, 16, v42
	v_pk_add_f32 v[16:17], v[90:91], v[16:17]
	v_and_b32_e32 v21, 0xffff0000, v42
	v_mul_f32_e32 v18, 0xbfb8aa3b, v16
	v_mul_f32_e32 v19, 0xbfb8aa3b, v17
	v_exp_f32_e32 v18, v18
	v_exp_f32_e32 v19, v19
	s_waitcnt lgkmcnt(0)
	v_cndmask_b32_e64 v46, v25, v49, s[4:5]
	v_add_f32_e32 v18, 1.0, v18
	v_add_f32_e32 v19, 1.0, v19
	v_rcp_f32_e32 v18, v18
	v_rcp_f32_e32 v19, v19
	s_nop 0
	v_pk_mul_f32 v[16:17], v[16:17], v[18:19]
	s_nop 0
	v_pk_mul_f32 v[14:15], v[14:15], v[16:17]
	v_lshlrev_b32_e32 v16, 16, v44
	v_and_b32_e32 v17, 0xffff0000, v44
	v_pk_mul_f32 v[16:17], v[76:77], v[16:17]
	v_lshlrev_b32_e32 v18, 16, v45
	v_and_b32_e32 v19, 0xffff0000, v45
	v_pk_fma_f32 v[16:17], v[68:69], v[20:21], v[16:17]
	v_lshlrev_b32_e32 v20, 16, v43
	v_pk_fma_f32 v[16:17], v[64:65], v[18:19], v[16:17]
	v_and_b32_e32 v21, 0xffff0000, v43
	v_pk_add_f32 v[16:17], v[72:73], v[16:17]
	s_nop 0
	v_mul_f32_e32 v18, 0xbfb8aa3b, v16
	v_mul_f32_e32 v19, 0xbfb8aa3b, v17
	v_exp_f32_e32 v18, v18
	v_exp_f32_e32 v19, v19
	v_add_f32_e32 v18, 1.0, v18
	v_add_f32_e32 v19, 1.0, v19
	v_rcp_f32_e32 v18, v18
	v_rcp_f32_e32 v19, v19
	s_nop 0
	v_pk_mul_f32 v[16:17], v[16:17], v[18:19]
	s_nop 0
	v_pk_mul_f32 v[16:17], v[8:9], v[16:17]
	v_lshlrev_b32_e32 v8, 16, v46
	v_and_b32_e32 v9, 0xffff0000, v46
	v_pk_mul_f32 v[8:9], v[78:79], v[8:9]
	v_lshlrev_b32_e32 v18, 16, v47
	v_and_b32_e32 v19, 0xffff0000, v47
	v_pk_fma_f32 v[8:9], v[70:71], v[20:21], v[8:9]
	s_nop 0
	v_pk_fma_f32 v[8:9], v[66:67], v[18:19], v[8:9]
	s_nop 0
	v_pk_add_f32 v[8:9], v[74:75], v[8:9]
	s_nop 0
	v_mul_f32_e32 v18, 0xbfb8aa3b, v8
	v_mul_f32_e32 v19, 0xbfb8aa3b, v9
	v_exp_f32_e32 v18, v18
	v_exp_f32_e32 v19, v19
	v_add_f32_e32 v18, 1.0, v18
	v_add_f32_e32 v19, 1.0, v19
	v_rcp_f32_e32 v18, v18
	v_rcp_f32_e32 v19, v19
	s_nop 0
	v_pk_mul_f32 v[8:9], v[8:9], v[18:19]
	s_nop 0
	v_pk_mul_f32 v[18:19], v[10:11], v[8:9]
	v_cvt_pk_bf16_f32 v8, v12, v13
	v_cvt_pk_bf16_f32 v9, v14, v15
	v_cvt_pk_bf16_f32 v10, v16, v17
	v_cvt_pk_bf16_f32 v11, v18, v19
	global_store_dwordx4 v[132:133], v[8:11], off offset:256
	ds_bpermute_b32 v8, v193, v32
	ds_bpermute_b32 v9, v193, v33
	ds_bpermute_b32 v10, v193, v34
	ds_bpermute_b32 v11, v193, v35
	s_waitcnt vmcnt(3)
	v_cndmask_b32_e64 v12, v39, 0, vcc
	s_waitcnt lgkmcnt(3)
	v_cndmask_b32_e64 v16, v8, v22, s[4:5]
	v_cndmask_b32_e64 v13, v38, 0, vcc
	v_cndmask_b32_e64 v15, v36, 0, vcc
	s_waitcnt lgkmcnt(2)
	v_cndmask_b32_e64 v17, v9, v23, s[4:5]
	v_lshlrev_b32_e32 v8, 16, v16
	v_and_b32_e32 v9, 0xffff0000, v16
	v_cndmask_b32_e64 v15, v26, v15, s[6:7]
	v_cndmask_b32_e64 v19, v28, v13, s[6:7]
	v_cndmask_b32_e64 v21, v29, v12, s[6:7]
	v_pk_mul_f32 v[8:9], v[92:93], v[8:9]
	v_lshlrev_b32_e32 v12, 16, v32
	v_and_b32_e32 v13, 0xffff0000, v32
	s_waitcnt lgkmcnt(1)
	v_cndmask_b32_e64 v18, v10, v24, s[4:5]
	s_waitcnt lgkmcnt(0)
	v_cndmask_b32_e64 v20, v11, v25, s[4:5]
	v_lshlrev_b32_e32 v10, 16, v15
	v_and_b32_e32 v11, 0xffff0000, v15
	v_pk_fma_f32 v[8:9], v[84:85], v[12:13], v[8:9]
	v_cndmask_b32_e64 v14, v37, 0, vcc
	v_pk_fma_f32 v[8:9], v[80:81], v[10:11], v[8:9]
	v_cndmask_b32_e64 v14, v27, v14, s[6:7]
	v_pk_add_f32 v[8:9], v[88:89], v[8:9]
	v_lshlrev_b32_e32 v12, 16, v33
	v_mul_f32_e32 v10, 0xbfb8aa3b, v8
	v_mul_f32_e32 v11, 0xbfb8aa3b, v9
	v_exp_f32_e32 v10, v10
	v_exp_f32_e32 v11, v11
	v_and_b32_e32 v13, 0xffff0000, v33
	s_andn2_b64 vcc, exec, s[68:69]
	v_add_f32_e32 v10, 1.0, v10
	v_add_f32_e32 v11, 1.0, v11
	v_rcp_f32_e32 v10, v10
	v_rcp_f32_e32 v11, v11
	s_nop 0
	v_pk_mul_f32 v[8:9], v[8:9], v[10:11]
	s_nop 0
	v_pk_mul_f32 v[4:5], v[4:5], v[8:9]
	v_lshlrev_b32_e32 v8, 16, v17
	v_and_b32_e32 v9, 0xffff0000, v17
	v_pk_mul_f32 v[8:9], v[94:95], v[8:9]
	v_lshlrev_b32_e32 v10, 16, v14
	v_and_b32_e32 v11, 0xffff0000, v14
	v_pk_fma_f32 v[8:9], v[86:87], v[12:13], v[8:9]
	v_lshlrev_b32_e32 v12, 16, v34
	v_pk_fma_f32 v[8:9], v[82:83], v[10:11], v[8:9]
	v_and_b32_e32 v13, 0xffff0000, v34
	v_pk_add_f32 v[8:9], v[90:91], v[8:9]
	s_nop 0
	v_mul_f32_e32 v10, 0xbfb8aa3b, v8
	v_mul_f32_e32 v11, 0xbfb8aa3b, v9
	v_exp_f32_e32 v10, v10
	v_exp_f32_e32 v11, v11
	v_add_f32_e32 v10, 1.0, v10
	v_add_f32_e32 v11, 1.0, v11
	v_rcp_f32_e32 v10, v10
	v_rcp_f32_e32 v11, v11
	s_nop 0
	v_pk_mul_f32 v[8:9], v[8:9], v[10:11]
	s_nop 0
	v_pk_mul_f32 v[6:7], v[6:7], v[8:9]
	v_lshlrev_b32_e32 v8, 16, v18
	v_and_b32_e32 v9, 0xffff0000, v18
	v_pk_mul_f32 v[8:9], v[76:77], v[8:9]
	v_lshlrev_b32_e32 v10, 16, v19
	v_and_b32_e32 v11, 0xffff0000, v19
	v_pk_fma_f32 v[8:9], v[68:69], v[12:13], v[8:9]
	v_lshlrev_b32_e32 v12, 16, v35
	v_pk_fma_f32 v[8:9], v[64:65], v[10:11], v[8:9]
	v_and_b32_e32 v13, 0xffff0000, v35
	v_pk_add_f32 v[8:9], v[72:73], v[8:9]
	s_nop 0
	v_mul_f32_e32 v10, 0xbfb8aa3b, v8
	v_mul_f32_e32 v11, 0xbfb8aa3b, v9
	v_exp_f32_e32 v10, v10
	v_exp_f32_e32 v11, v11
	v_add_f32_e32 v10, 1.0, v10
	v_add_f32_e32 v11, 1.0, v11
	v_rcp_f32_e32 v10, v10
	v_rcp_f32_e32 v11, v11
	s_nop 0
	v_pk_mul_f32 v[8:9], v[8:9], v[10:11]
	s_nop 0
	v_pk_mul_f32 v[8:9], v[0:1], v[8:9]
	v_lshlrev_b32_e32 v0, 16, v20
	v_and_b32_e32 v1, 0xffff0000, v20
	v_pk_mul_f32 v[0:1], v[78:79], v[0:1]
	v_lshlrev_b32_e32 v10, 16, v21
	v_and_b32_e32 v11, 0xffff0000, v21
	v_pk_fma_f32 v[0:1], v[70:71], v[12:13], v[0:1]
	s_nop 0
	v_pk_fma_f32 v[0:1], v[66:67], v[10:11], v[0:1]
	s_nop 0
	v_pk_add_f32 v[0:1], v[74:75], v[0:1]
	s_nop 0
	v_mul_f32_e32 v10, 0xbfb8aa3b, v0
	v_mul_f32_e32 v11, 0xbfb8aa3b, v1
	v_exp_f32_e32 v10, v10
	v_exp_f32_e32 v11, v11
	v_add_f32_e32 v10, 1.0, v10
	v_add_f32_e32 v11, 1.0, v11
	v_rcp_f32_e32 v10, v10
	v_rcp_f32_e32 v11, v11
	s_nop 0
	v_pk_mul_f32 v[0:1], v[0:1], v[10:11]
	s_nop 0
	v_pk_mul_f32 v[10:11], v[2:3], v[0:1]
	v_cvt_pk_bf16_f32 v0, v4, v5
	v_cvt_pk_bf16_f32 v1, v6, v7
	v_cvt_pk_bf16_f32 v2, v8, v9
	v_cvt_pk_bf16_f32 v3, v10, v11
	global_store_dwordx4 v[112:113], v[0:3], off offset:256
	s_cbranch_vccnz .LBB0_1053
	s_andn2_b64 vcc, exec, s[36:37]
	s_cbranch_vccnz .LBB0_1052
	s_barrier
	s_branch .LBB0_1052
